# combined: norm-loop consolidation + GLA norm1 parameter ring (all 8 rounds, store-data hazard padded) + K-image swizzle in the retention scan + scan store-wait removal + v_cvt_pk_bf16_f32 instead of t
# baseline (speedup 1.0000x reference)
; __device__ __forceinline__ void unpack8(const v4u& w, float (&f)[8]) { f[0] = bflo(w.x); f[1] = bfhi(w.x); f[2] = bflo(w.y); f[3] = bfhi(w.y); f[4] = bflo(w.z); f[5] = bfhi(w.z); f[6] = bflo(w.w); f[7] = bfhi(w.w); }
; template <bool ZP, bool XF32, bool OUT8 = false>
; __device__ __forceinline__ void norm_phase(LAS unsigned char* lds, const void* xin, const float* gain, const float* sh, const float* sc, bf16* hout, const float* wzt, float* zout, int lane, int wave, int vcu, int G) {
;     ...
;         const int m0 = xdeal ? 2048 * (gw >> 8) + 2 * (gw & 255) + 512 * it_ : 2 * gw + it_ * 2 * NGW;
;         if (m0 >= M) break;
;         f32x4 v[2][4][2]; float ss[2] = {0.f, 0.f};
; #pragma unroll
;         for (int r = 0; r < 2; ++r)
; #pragma unroll
;             for (int j = 0; j < 4; ++j) {
;                 if constexpr (XF32) { const float* xr = (const float*)xin + (size_t)(m0 + r) * D + 8 * lane; v[r][j][0] = *(const f32x4*)(xr + 512 * j); v[r][j][1] = *(const f32x4*)(xr + 512 * j + 4); }
;                 else { float f[8]; unpack8(*(const v4u*)((const bf16*)xin + (size_t)(m0 + r) * D + 8 * lane + 512 * j), f); v[r][j][0] = (f32x4){f[0], f[1], f[2], f[3]}; v[r][j][1] = (f32x4){f[4], f[5], f[6], f[7]}; } }
; #pragma unroll
;         for (int r = 0; r < 2; ++r)
; #pragma unroll
;             for (int j = 0; j < 4; ++j)
; #pragma unroll
;                 for (int e = 0; e < 4; ++e) ss[r] += v[r][j][0][e] * v[r][j][0][e] + v[r][j][1][e] * v[r][j][1][e];
; #pragma unroll
;         for (int r = 0; r < 2; ++r) { const int m = m0 + r, b = m >> 11;
;             const float rstd = rsqrtf(wave_sum(ss[r]) * (1.0f / D) + EPS);
; #pragma unroll
;             for (int j = 0; j < 4; ++j) { const int col = 512 * j + 8 * lane;
; #pragma unroll
;                 for (int q = 0; q < 2; ++q) { const f32x4 gg = *(const f32x4*)(gain + col + 4 * q), s1 = *(const f32x4*)(sc + (size_t)b * MODW + col + 4 * q), s0 = *(const f32x4*)(sh + (size_t)b * MODW + col + 4 * q);
.LBB0_1557:
	s_ashr_i32 s19, s18, 31
	s_lshl_b64 s[24:25], s[18:19], 12
	s_add_i32 s20, s18, 1
	v_lshl_add_u64 v[2:3], v[58:59], 0, s[24:25]
	s_ashr_i32 s21, s20, 31
	global_load_dwordx4 v[18:21], v[2:3], off offset:1024
	global_load_dwordx4 v[10:13], v[2:3], off offset:3072
	global_load_dwordx4 v[14:17], v[2:3], off
	global_load_dwordx4 v[46:49], v[2:3], off offset:2048
	s_lshl_b64 s[22:23], s[20:21], 12
	s_waitcnt lgkmcnt(1)
	v_lshl_add_u64 v[6:7], v[58:59], 0, s[22:23]
	global_load_dwordx4 v[50:53], v[6:7], off offset:1024
	global_load_dwordx4 v[54:57], v[6:7], off
	global_load_dwordx4 v[2:5], v[6:7], off offset:3072
	global_load_dwordx4 v[74:77], v[6:7], off offset:2048
	s_ashr_i32 s0, s18, 11
	s_mul_hi_i32 s1, s0, 0xc000
	s_mul_i32 s0, s0, 0xc000
	s_add_u32 s26, s17, s0
	s_addc_u32 s27, s30, s1
	s_add_u32 s28, s31, s0
	s_addc_u32 s29, s34, s1
	v_and_b32_e32 v1, 64, v216
	v_add_u32_e32 v1, 64, v1
	s_ashr_i32 s0, s20, 11
	s_mul_hi_i32 s1, s0, 0xc000
	s_mul_i32 s0, s0, 0xc000
	s_waitcnt vmcnt(7)
	v_and_b32_e32 v7, 0xffff0000, v18
	s_waitcnt vmcnt(6)
	v_and_b32_e32 v40, 0xffff0000, v12
	v_lshlrev_b32_e32 v41, 16, v12
	v_and_b32_e32 v44, 0xffff0000, v13
	v_lshlrev_b32_e32 v45, 16, v13
	v_and_b32_e32 v38, 0xffff0000, v10
	v_lshlrev_b32_e32 v39, 16, v10
	v_and_b32_e32 v42, 0xffff0000, v11
	v_lshlrev_b32_e32 v43, 16, v11
	s_waitcnt vmcnt(5)
	v_lshlrev_b32_e32 v25, 16, v16
	v_and_b32_e32 v29, 0xffff0000, v16
	s_waitcnt vmcnt(4)
	v_lshlrev_b32_e32 v125, 16, v46
	v_and_b32_e32 v127, 0xffff0000, v46
	v_lshlrev_b32_e32 v129, 16, v47
	v_and_b32_e32 v131, 0xffff0000, v47
	v_lshlrev_b32_e32 v133, 16, v48
	v_and_b32_e32 v137, 0xffff0000, v48
	v_lshlrev_b32_e32 v135, 16, v49
	v_and_b32_e32 v139, 0xffff0000, v49
	v_pk_mul_f32 v[46:47], v[40:41], v[40:41]
	v_pk_mul_f32 v[48:49], v[44:45], v[44:45]
	s_waitcnt vmcnt(2)
	v_lshlrev_b32_e32 v24, 16, v56
	v_and_b32_e32 v28, 0xffff0000, v56
	v_lshlrev_b32_e32 v23, 16, v14
	v_and_b32_e32 v27, 0xffff0000, v14
	v_lshlrev_b32_e32 v31, 16, v17
	v_lshlrev_b32_e32 v22, 16, v54
	v_and_b32_e32 v26, 0xffff0000, v54
	v_lshlrev_b32_e32 v30, 16, v57
	v_pk_fma_f32 v[78:79], v[38:39], v[38:39], v[46:47]
	v_pk_fma_f32 v[88:89], v[42:43], v[42:43], v[48:49]
	v_pk_mul_f32 v[46:47], v[24:25], v[24:25]
	v_pk_mul_f32 v[48:49], v[28:29], v[28:29]
	v_lshlrev_b32_e32 v33, 16, v15
	v_and_b32_e32 v37, 0xffff0000, v17
	v_and_b32_e32 v6, 0xffff0000, v50
	v_lshlrev_b32_e32 v32, 16, v55
	v_and_b32_e32 v36, 0xffff0000, v57
	v_lshlrev_b32_e32 v10, 16, v50
	v_lshlrev_b32_e32 v14, 16, v51
	v_and_b32_e32 v16, 0xffff0000, v51
	v_pk_mul_f32 v[50:51], v[30:31], v[30:31]
	v_pk_fma_f32 v[46:47], v[22:23], v[22:23], v[46:47]
	v_pk_fma_f32 v[48:49], v[26:27], v[26:27], v[48:49]
	s_waitcnt lgkmcnt(0)
	v_and_b32_e32 v9, 0xffff0000, v20
	v_and_b32_e32 v35, 0xffff0000, v15
	v_lshlrev_b32_e32 v11, 16, v18
	v_lshlrev_b32_e32 v13, 16, v20
	v_and_b32_e32 v8, 0xffff0000, v52
	v_and_b32_e32 v34, 0xffff0000, v55
	v_lshlrev_b32_e32 v12, 16, v52
	v_lshlrev_b32_e32 v18, 16, v53
	v_and_b32_e32 v20, 0xffff0000, v53
	v_pk_mul_f32 v[52:53], v[36:37], v[36:37]
	v_pk_fma_f32 v[50:51], v[32:33], v[32:33], v[50:51]
	v_pk_add_f32 v[46:47], v[46:47], v[48:49]
	v_pk_fma_f32 v[48:49], v[34:35], v[34:35], v[52:53]
	v_pk_add_f32 v[46:47], v[50:51], v[46:47]
	v_lshlrev_b32_e32 v15, 16, v19
	v_pk_add_f32 v[46:47], v[48:49], v[46:47]
	v_pk_mul_f32 v[48:49], v[12:13], v[12:13]
	v_and_b32_e32 v17, 0xffff0000, v19
	v_pk_fma_f32 v[48:49], v[10:11], v[10:11], v[48:49]
	v_lshlrev_b32_e32 v19, 16, v21
	v_pk_add_f32 v[46:47], v[48:49], v[46:47]
	v_pk_mul_f32 v[48:49], v[8:9], v[8:9]
	v_and_b32_e32 v21, 0xffff0000, v21
	v_pk_fma_f32 v[48:49], v[6:7], v[6:7], v[48:49]
	s_waitcnt vmcnt(1)
	v_and_b32_e32 v140, 0xffff0000, v4
	v_pk_add_f32 v[46:47], v[48:49], v[46:47]
	v_pk_mul_f32 v[48:49], v[18:19], v[18:19]
	v_lshlrev_b32_e32 v141, 16, v4
	v_pk_fma_f32 v[48:49], v[14:15], v[14:15], v[48:49]
	s_waitcnt vmcnt(0)
	v_lshlrev_b32_e32 v132, 16, v76
	v_pk_add_f32 v[46:47], v[48:49], v[46:47]
	v_pk_mul_f32 v[48:49], v[20:21], v[20:21]
	v_and_b32_e32 v142, 0xffff0000, v2
	v_lshlrev_b32_e32 v143, 16, v2
	v_lshlrev_b32_e32 v124, 16, v74
	v_pk_mul_f32 v[54:55], v[140:141], v[140:141]
	v_pk_fma_f32 v[48:49], v[16:17], v[16:17], v[48:49]
	v_pk_mul_f32 v[56:57], v[132:133], v[132:133]
	v_and_b32_e32 v136, 0xffff0000, v76
	v_pk_fma_f32 v[90:91], v[142:143], v[142:143], v[54:55]
	v_pk_add_f32 v[54:55], v[48:49], v[46:47]
	v_pk_fma_f32 v[56:57], v[124:125], v[124:125], v[56:57]
	v_and_b32_e32 v126, 0xffff0000, v74
	v_pk_add_f32 v[54:55], v[56:57], v[54:55]
	v_pk_mul_f32 v[56:57], v[136:137], v[136:137]
	v_lshlrev_b32_e32 v134, 16, v77
	v_pk_fma_f32 v[56:57], v[126:127], v[126:127], v[56:57]
	v_lshlrev_b32_e32 v128, 16, v75
	v_pk_add_f32 v[54:55], v[56:57], v[54:55]
	v_pk_mul_f32 v[56:57], v[134:135], v[134:135]
	v_and_b32_e32 v138, 0xffff0000, v77
	v_pk_fma_f32 v[56:57], v[128:129], v[128:129], v[56:57]
	v_and_b32_e32 v130, 0xffff0000, v75
	v_pk_add_f32 v[54:55], v[56:57], v[54:55]
	v_pk_mul_f32 v[56:57], v[138:139], v[138:139]
	s_add_u32 s98, s17, s0
	s_addc_u32 s99, s30, s1
	s_add_u32 s100, s31, s0
	s_addc_u32 s101, s34, s1
	global_load_dwordx4 v[150:153], v213, s[26:27] offset:16
	global_load_dwordx4 v[154:157], v213, s[26:27]
	global_load_dwordx4 v[158:161], v[62:63], off offset:16
	global_load_dwordx4 v[162:165], v[62:63], off
	global_load_dwordx4 v[166:169], v213, s[28:29] offset:16
	global_load_dwordx4 v[170:173], v213, s[28:29]
	global_load_dwordx4 v[174:177], v[64:65], off
	global_load_dwordx4 v[178:181], v213, s[26:27] offset:2048
	global_load_dwordx4 v[182:185], v213, s[28:29] offset:2048
	global_load_dwordx4 v[186:189], v[64:65], off offset:16
	global_load_dwordx4 v[190:193], v213, s[26:27] offset:2064
	global_load_dwordx4 v[194:197], v213, s[28:29] offset:2064
	v_pk_fma_f32 v[56:57], v[130:131], v[130:131], v[56:57]
	v_and_b32_e32 v146, 0xffff0000, v5
	v_pk_add_f32 v[54:55], v[56:57], v[54:55]
	v_mov_b32_e32 v56, v91
	v_mov_b32_e32 v57, v79
	v_pk_add_f32 v[92:93], v[56:57], v[54:55]
	v_lshlrev_b32_e32 v147, 16, v5
	v_xor_b32_e32 v4, 1, v216
	v_and_b32_e32 v144, 0xffff0000, v3
	v_lshlrev_b32_e32 v145, 16, v3
	v_pk_mul_f32 v[2:3], v[146:147], v[146:147]
	v_cmp_lt_i32_e32 vcc, v4, v1
	v_pk_fma_f32 v[2:3], v[144:145], v[144:145], v[2:3]
	v_mov_b32_e32 v91, v78
	v_cndmask_b32_e32 v4, v216, v4, vcc
	v_lshlrev_b32_e32 v217, 2, v4
	v_pk_add_f32 v[4:5], v[90:91], v[92:93]
	v_mov_b32_e32 v78, v3
	v_mov_b32_e32 v79, v89
	v_pk_add_f32 v[4:5], v[78:79], v[4:5]
	v_mov_b32_e32 v3, v88
	v_pk_add_f32 v[2:3], v[2:3], v[4:5]
	ds_bpermute_b32 v5, v217, v3
	ds_bpermute_b32 v4, v217, v2
	v_xor_b32_e32 v78, 2, v216
	v_cmp_lt_i32_e32 vcc, v78, v1
	v_mov_b32_e32 v90, v23
	v_mov_b32_e32 v91, v27
	v_cndmask_b32_e32 v78, v216, v78, vcc
	v_lshlrev_b32_e32 v218, 2, v78
	s_waitcnt lgkmcnt(0)
; __device__ __forceinline__ unsigned pk2(float lo, float hi) { return f2bf(lo) | (f2bf(hi) << 16); }
; __device__ __forceinline__ float wave_sum(float v) {
; #pragma unroll
;     for (int o = 1; o < 64; o <<= 1) v += __shfl_xor(v, o);
;     return v;
; template <bool ZP, bool XF32, bool OUT8 = false>
; __device__ __forceinline__ void norm_phase(LAS unsigned char* lds, const void* xin, const float* gain, const float* sh, const float* sc, bf16* hout, const float* wzt, float* zout, int lane, int wave, int vcu, int G) {
;     ...
;         for (int r = 0; r < 2; ++r) { const int m = m0 + r, b = m >> 11;
;             const float rstd = rsqrtf(wave_sum(ss[r]) * (1.0f / D) + EPS);
; #pragma unroll
;             for (int j = 0; j < 4; ++j) { const int col = 512 * j + 8 * lane;
; #pragma unroll
;                 for (int q = 0; q < 2; ++q) { const f32x4 gg = *(const f32x4*)(gain + col + 4 * q), s1 = *(const f32x4*)(sc + (size_t)b * MODW + col + 4 * q), s0 = *(const f32x4*)(sh + (size_t)b * MODW + col + 4 * q);
;                     v[r][j][q] = (v[r][j][q] * rstd * gg) * (s1 + 1.0f) + s0; }
;                 if constexpr (OUT8) { *(v2u*)((unsigned char*)hout + (size_t)m * D + col) = pack8_fp8(v[r][j][0][0], v[r][j][0][1], v[r][j][0][2], v[r][j][0][3], v[r][j][1][0], v[r][j][1][1], v[r][j][1][2], v[r][j][1][3], FP8_ASCALE); }
;                 else { v4u o; o.x = pk2(v[r][j][0][0], v[r][j][0][1]); o.y = pk2(v[r][j][0][2], v[r][j][0][3]); o.z = pk2(v[r][j][1][0], v[r][j][1][1]); o.w = pk2(v[r][j][1][2], v[r][j][1][3]);
;                     *(v4u*)(hout + (size_t)m * D + col) = o; } }
	v_pk_add_f32 v[2:3], v[2:3], v[4:5]
	ds_bpermute_b32 v5, v218, v3
	ds_bpermute_b32 v4, v218, v2
	v_xor_b32_e32 v78, 4, v216
	v_cmp_lt_i32_e32 vcc, v78, v1
	v_mov_b32_e32 v79, v35
	v_mov_b32_e32 v110, v133
	v_cndmask_b32_e32 v78, v216, v78, vcc
	v_lshlrev_b32_e32 v219, 2, v78
	s_waitcnt lgkmcnt(0)
	v_pk_add_f32 v[2:3], v[2:3], v[4:5]
	ds_bpermute_b32 v5, v219, v3
	ds_bpermute_b32 v4, v219, v2
	v_xor_b32_e32 v78, 8, v216
	v_cmp_lt_i32_e32 vcc, v78, v1
	v_mov_b32_e32 v111, v137
	v_mov_b32_e32 v108, v135
	v_cndmask_b32_e32 v78, v216, v78, vcc
	v_lshlrev_b32_e32 v220, 2, v78
	s_waitcnt lgkmcnt(0)
	v_pk_add_f32 v[2:3], v[2:3], v[4:5]
	ds_bpermute_b32 v5, v220, v3
	ds_bpermute_b32 v4, v220, v2
	v_xor_b32_e32 v78, 16, v216
	v_cmp_lt_i32_e32 vcc, v78, v1
	v_mov_b32_e32 v109, v139
	v_pk_mov_b32 v[42:43], v[42:43], v[42:43] op_sel:[1,0]
	v_cndmask_b32_e32 v78, v216, v78, vcc
	v_lshlrev_b32_e32 v221, 2, v78
	s_waitcnt lgkmcnt(0)
	v_pk_add_f32 v[2:3], v[2:3], v[4:5]
	ds_bpermute_b32 v5, v221, v3
	ds_bpermute_b32 v4, v221, v2
	v_xor_b32_e32 v78, 32, v216
	v_cmp_lt_i32_e32 vcc, v78, v1
	v_pk_mov_b32 v[44:45], v[44:45], v[44:45] op_sel:[1,0]
	v_mov_b32_e32 v23, v26
	v_cndmask_b32_e32 v1, v216, v78, vcc
	v_lshlrev_b32_e32 v222, 2, v1
	s_waitcnt lgkmcnt(0)
	v_pk_add_f32 v[2:3], v[2:3], v[4:5]
	ds_bpermute_b32 v5, v222, v3
	ds_bpermute_b32 v4, v222, v2
	v_mov_b32_e32 v78, v33
	v_mov_b32_e32 v33, v34
	v_mov_b32_e32 v135, v138
	v_mov_b32_e32 v133, v136
	s_waitcnt lgkmcnt(0)
	v_pk_add_f32 v[2:3], v[2:3], v[4:5]
	v_lshl_add_u64 v[4:5], v[70:71], 0, s[24:25]
	v_pk_fma_f32 v[2:3], v[2:3], s[16:17], v[72:73] op_sel_hi:[1,0,0]
	s_add_u32 s24, s17, s0
	v_mul_f32_e32 v1, 0x4b800000, v3
	v_cmp_gt_f32_e32 vcc, s40, v3
	s_waitcnt vmcnt(6)
	s_nop 1
	v_mov_b64_e32 v[46:47], v[150:151]
	v_mov_b64_e32 v[48:49], v[152:153]
	v_mov_b64_e32 v[50:51], v[154:155]
	v_mov_b64_e32 v[52:53], v[156:157]
	v_mov_b64_e32 v[54:55], v[158:159]
	v_mov_b64_e32 v[56:57], v[160:161]
	v_mov_b64_e32 v[74:75], v[162:163]
	v_mov_b64_e32 v[76:77], v[164:165]
	v_mov_b64_e32 v[80:81], v[166:167]
	v_mov_b64_e32 v[82:83], v[168:169]
	v_mov_b64_e32 v[84:85], v[170:171]
	v_mov_b64_e32 v[86:87], v[172:173]
	global_load_dwordx4 v[150:153], v[66:67], off
	global_load_dwordx4 v[154:157], v214, s[26:27]
	global_load_dwordx4 v[158:161], v214, s[28:29]
	global_load_dwordx4 v[162:165], v[66:67], off offset:16
	global_load_dwordx4 v[166:169], v214, s[26:27] offset:16
	global_load_dwordx4 v[170:173], v214, s[28:29] offset:16
	v_pk_add_f32 v[88:89], v[46:47], 1.0 op_sel_hi:[1,0]
	v_pk_add_f32 v[50:51], v[50:51], 1.0 op_sel_hi:[1,0]
	v_cndmask_b32_e32 v1, v3, v1, vcc
	v_rsq_f32_e32 v1, v1
	v_pk_add_f32 v[52:53], v[52:53], 1.0 op_sel_hi:[1,0]
	v_pk_add_f32 v[48:49], v[48:49], 1.0 op_sel_hi:[1,0]
	s_addc_u32 s25, s30, s1
	v_mul_f32_e32 v3, 0x45800000, v1
	v_cndmask_b32_e32 v46, v1, v3, vcc
	v_pk_mul_f32 v[90:91], v[46:47], v[90:91] op_sel_hi:[0,1]
	v_pk_mul_f32 v[78:79], v[46:47], v[78:79] op_sel_hi:[0,1]
	v_pk_mul_f32 v[90:91], v[74:75], v[90:91]
	v_pk_mul_f32 v[74:75], v[76:77], v[78:79]
	v_pk_fma_f32 v[78:79], v[50:51], v[90:91], v[84:85]
	v_mov_b32_e32 v50, v31
	v_mov_b32_e32 v51, v37
	v_pk_mul_f32 v[50:51], v[46:47], v[50:51] op_sel_hi:[0,1]
	v_pk_fma_f32 v[74:75], v[52:53], v[74:75], v[86:87]
	v_mov_b32_e32 v52, v25
	v_mov_b32_e32 v53, v29
	v_pk_mul_f32 v[50:51], v[56:57], v[50:51]
	v_pk_mul_f32 v[52:53], v[46:47], v[52:53] op_sel_hi:[0,1]
	v_pk_fma_f32 v[76:77], v[48:49], v[50:51], v[82:83]
	v_cvt_pk_bf16_f32 v48, v78, v79
	v_pk_mul_f32 v[52:53], v[54:55], v[52:53]
	v_pk_fma_f32 v[82:83], v[88:89], v[52:53], v[80:81]
	v_cvt_pk_bf16_f32 v49, v74, v75
	v_cvt_pk_bf16_f32 v50, v82, v83
	v_cvt_pk_bf16_f32 v51, v76, v77
	global_store_dwordx4 v[4:5], v[48:51], off
	s_nop 0
	v_mov_b32_e32 v80, v11
	v_mov_b32_e32 v81, v7
	v_pk_mul_f32 v[80:81], v[46:47], v[80:81] op_sel_hi:[0,1]
	v_mov_b32_e32 v56, v15
	v_mov_b32_e32 v57, v17
	v_pk_mul_f32 v[56:57], v[46:47], v[56:57] op_sel_hi:[0,1]
	v_pk_mul_f32 v[108:109], v[46:47], v[108:109] op_sel_hi:[0,1]
	v_pk_mul_f32 v[44:45], v[46:47], v[44:45] op_sel_hi:[0,1]
	v_cmp_gt_f32_e32 vcc, s40, v2
	v_mov_b32_e32 v31, v36
	v_mov_b32_e32 v25, v28
	v_mov_b32_e32 v136, v143
	v_mov_b32_e32 v137, v142
	v_mov_b32_e32 v138, v141
	v_mov_b32_e32 v139, v140
	v_pk_mov_b32 v[144:145], v[144:145], v[144:145] op_sel:[1,0]
	v_pk_mov_b32 v[146:147], v[146:147], v[146:147] op_sel:[1,0]
	s_waitcnt vmcnt(6)
	s_nop 1
	v_mov_b64_e32 v[48:49], v[174:175]
	v_mov_b64_e32 v[50:51], v[176:177]
	v_mov_b64_e32 v[52:53], v[178:179]
	v_mov_b64_e32 v[54:55], v[180:181]
	v_mov_b64_e32 v[84:85], v[182:183]
	v_mov_b64_e32 v[86:87], v[184:185]
	v_mov_b64_e32 v[88:89], v[186:187]
	v_mov_b64_e32 v[90:91], v[188:189]
	v_mov_b64_e32 v[92:93], v[190:191]
	v_mov_b64_e32 v[94:95], v[192:193]
	v_mov_b64_e32 v[96:97], v[194:195]
	v_mov_b64_e32 v[98:99], v[196:197]
	global_load_dwordx4 v[174:177], v[68:69], off
	global_load_dwordx4 v[178:181], v215, s[26:27]
	global_load_dwordx4 v[182:185], v[68:69], off offset:16
	global_load_dwordx4 v[186:189], v215, s[26:27] offset:16
	global_load_dwordx4 v[190:193], v215, s[28:29]
	global_load_dwordx4 v[194:197], v215, s[28:29] offset:16
	v_pk_mul_f32 v[48:49], v[48:49], v[80:81]
	v_pk_add_f32 v[52:53], v[52:53], 1.0 op_sel_hi:[1,0]
	v_pk_mul_f32 v[50:51], v[50:51], v[56:57]
	v_pk_fma_f32 v[84:85], v[52:53], v[48:49], v[84:85]
	v_mov_b32_e32 v48, v19
	v_mov_b32_e32 v49, v21
	v_pk_add_f32 v[54:55], v[54:55], 1.0 op_sel_hi:[1,0]
	v_pk_mul_f32 v[48:49], v[46:47], v[48:49] op_sel_hi:[0,1]
	v_pk_fma_f32 v[80:81], v[54:55], v[50:51], v[86:87]
	v_mov_b32_e32 v50, v13
	v_mov_b32_e32 v51, v9
	v_pk_mul_f32 v[48:49], v[90:91], v[48:49]
	v_pk_add_f32 v[52:53], v[94:95], 1.0 op_sel_hi:[1,0]
	v_pk_mul_f32 v[50:51], v[46:47], v[50:51] op_sel_hi:[0,1]
	v_pk_fma_f32 v[86:87], v[52:53], v[48:49], v[98:99]
	v_cvt_pk_bf16_f32 v48, v84, v85
	v_pk_mul_f32 v[50:51], v[88:89], v[50:51]
	v_pk_add_f32 v[54:55], v[92:93], 1.0 op_sel_hi:[1,0]
	v_pk_fma_f32 v[88:89], v[54:55], v[50:51], v[96:97]
	v_cvt_pk_bf16_f32 v49, v80, v81
	v_cvt_pk_bf16_f32 v50, v88, v89
	v_cvt_pk_bf16_f32 v51, v86, v87
	global_store_dwordx4 v[4:5], v[48:51], off offset:1024
	s_nop 0
	v_mov_b32_e32 v56, v129
	v_mov_b32_e32 v57, v131
	v_mov_b32_e32 v90, v125
	v_mov_b32_e32 v91, v127
	v_pk_mul_f32 v[56:57], v[46:47], v[56:57] op_sel_hi:[0,1]
	v_pk_mul_f32 v[90:91], v[46:47], v[90:91] op_sel_hi:[0,1]
	v_mov_b32_e32 v19, v20
	v_mov_b32_e32 v129, v130
	v_mov_b32_e32 v125, v126
	s_waitcnt vmcnt(6)
; __device__ __forceinline__ unsigned pk2(float lo, float hi) { return f2bf(lo) | (f2bf(hi) << 16); }
; template <bool ZP, bool XF32, bool OUT8 = false>
; __device__ __forceinline__ void norm_phase(LAS unsigned char* lds, const void* xin, const float* gain, const float* sh, const float* sc, bf16* hout, const float* wzt, float* zout, int lane, int wave, int vcu, int G) {
;     ...
;         for (int r = 0; r < 2; ++r) { const int m = m0 + r, b = m >> 11;
;             const float rstd = rsqrtf(wave_sum(ss[r]) * (1.0f / D) + EPS);
; #pragma unroll
;             for (int j = 0; j < 4; ++j) { const int col = 512 * j + 8 * lane;
; #pragma unroll
;                 for (int q = 0; q < 2; ++q) { const f32x4 gg = *(const f32x4*)(gain + col + 4 * q), s1 = *(const f32x4*)(sc + (size_t)b * MODW + col + 4 * q), s0 = *(const f32x4*)(sh + (size_t)b * MODW + col + 4 * q);
;                     v[r][j][q] = (v[r][j][q] * rstd * gg) * (s1 + 1.0f) + s0; }
;                 if constexpr (OUT8) { *(v2u*)((unsigned char*)hout + (size_t)m * D + col) = pack8_fp8(v[r][j][0][0], v[r][j][0][1], v[r][j][0][2], v[r][j][0][3], v[r][j][1][0], v[r][j][1][1], v[r][j][1][2], v[r][j][1][3], FP8_ASCALE); }
;                 else { v4u o; o.x = pk2(v[r][j][0][0], v[r][j][0][1]); o.y = pk2(v[r][j][0][2], v[r][j][0][3]); o.z = pk2(v[r][j][1][0], v[r][j][1][1]); o.w = pk2(v[r][j][1][2], v[r][j][1][3]);
;                     *(v4u*)(hout + (size_t)m * D + col) = o; } }
	s_nop 1
	v_mov_b64_e32 v[48:49], v[150:151]
	v_mov_b64_e32 v[50:51], v[152:153]
	v_mov_b64_e32 v[52:53], v[154:155]
	v_mov_b64_e32 v[54:55], v[156:157]
	v_mov_b64_e32 v[92:93], v[158:159]
	v_mov_b64_e32 v[94:95], v[160:161]
	v_mov_b64_e32 v[96:97], v[162:163]
	v_mov_b64_e32 v[98:99], v[164:165]
	v_mov_b64_e32 v[100:101], v[166:167]
	v_mov_b64_e32 v[102:103], v[168:169]
	v_mov_b64_e32 v[104:105], v[170:171]
	v_mov_b64_e32 v[106:107], v[172:173]
	global_load_dwordx4 v[150:153], v[62:63], off
	global_load_dwordx4 v[154:157], v213, s[98:99]
	global_load_dwordx4 v[158:161], v[62:63], off offset:16
	global_load_dwordx4 v[162:165], v213, s[98:99] offset:16
	global_load_dwordx4 v[166:169], v213, s[100:101]
	global_load_dwordx4 v[170:173], v213, s[100:101] offset:16
	v_pk_mul_f32 v[48:49], v[48:49], v[90:91]
	v_pk_mul_f32 v[50:51], v[50:51], v[56:57]
	v_pk_add_f32 v[54:55], v[54:55], 1.0 op_sel_hi:[1,0]
	v_pk_add_f32 v[52:53], v[52:53], 1.0 op_sel_hi:[1,0]
	v_pk_fma_f32 v[90:91], v[54:55], v[50:51], v[94:95]
	v_pk_fma_f32 v[94:95], v[52:53], v[48:49], v[92:93]
	v_pk_mul_f32 v[48:49], v[46:47], v[110:111] op_sel_hi:[0,1]
	v_pk_mul_f32 v[48:49], v[96:97], v[48:49]
	v_pk_add_f32 v[54:55], v[100:101], 1.0 op_sel_hi:[1,0]
	v_pk_fma_f32 v[96:97], v[54:55], v[48:49], v[104:105]
	v_cvt_pk_bf16_f32 v48, v94, v95
	v_cvt_pk_bf16_f32 v49, v90, v91
	v_pk_mul_f32 v[50:51], v[98:99], v[108:109]
	v_pk_add_f32 v[52:53], v[102:103], 1.0 op_sel_hi:[1,0]
	v_pk_fma_f32 v[92:93], v[52:53], v[50:51], v[106:107]
	v_cvt_pk_bf16_f32 v50, v96, v97
	v_cvt_pk_bf16_f32 v51, v92, v93
	global_store_dwordx4 v[4:5], v[48:51], off offset:2048
	s_nop 0
	v_mov_b32_e32 v56, v39
	v_mov_b32_e32 v57, v38
	v_mov_b32_e32 v38, v41
	v_mov_b32_e32 v39, v40
	v_pk_mul_f32 v[40:41], v[46:47], v[42:43] op_sel_hi:[0,1]
	v_pk_mul_f32 v[42:43], v[46:47], v[56:57] op_sel_hi:[0,1]
	v_pk_mul_f32 v[38:39], v[46:47], v[38:39] op_sel_hi:[0,1]
	s_add_u32 s26, s31, s0
	s_addc_u32 s27, s34, s1
	s_waitcnt vmcnt(6)
	s_nop 1
	v_mov_b64_e32 v[48:49], v[174:175]
	v_mov_b64_e32 v[50:51], v[176:177]
	v_mov_b64_e32 v[52:53], v[178:179]
	v_mov_b64_e32 v[54:55], v[180:181]
	v_mov_b64_e32 v[98:99], v[182:183]
	v_mov_b64_e32 v[100:101], v[184:185]
	v_mov_b64_e32 v[102:103], v[186:187]
	v_mov_b64_e32 v[104:105], v[188:189]
	v_mov_b64_e32 v[106:107], v[190:191]
	v_mov_b64_e32 v[108:109], v[192:193]
	v_mov_b64_e32 v[110:111], v[194:195]
	v_mov_b64_e32 v[112:113], v[196:197]
	global_load_dwordx4 v[174:177], v[64:65], off
	global_load_dwordx4 v[178:181], v213, s[98:99] offset:2048
	global_load_dwordx4 v[182:185], v[64:65], off offset:16
	global_load_dwordx4 v[186:189], v213, s[98:99] offset:2064
	global_load_dwordx4 v[190:193], v213, s[100:101] offset:2048
	global_load_dwordx4 v[194:197], v213, s[100:101] offset:2064
	v_pk_mul_f32 v[42:43], v[48:49], v[42:43]
	v_pk_mul_f32 v[40:41], v[50:51], v[40:41]
	v_pk_add_f32 v[46:47], v[54:55], 1.0 op_sel_hi:[1,0]
	v_pk_add_f32 v[48:49], v[52:53], 1.0 op_sel_hi:[1,0]
	v_pk_mul_f32 v[38:39], v[38:39], v[98:99]
	v_pk_mul_f32 v[44:45], v[44:45], v[100:101]
	v_pk_add_f32 v[50:51], v[104:105], 1.0 op_sel_hi:[1,0]
	v_pk_add_f32 v[52:53], v[102:103], 1.0 op_sel_hi:[1,0]
	v_pk_fma_f32 v[100:101], v[40:41], v[46:47], v[108:109]
	v_pk_fma_f32 v[104:105], v[42:43], v[48:49], v[106:107]
	v_pk_fma_f32 v[102:103], v[44:45], v[50:51], v[112:113]
	v_pk_fma_f32 v[106:107], v[38:39], v[52:53], v[110:111]
	v_cvt_pk_bf16_f32 v38, v104, v105
	v_cvt_pk_bf16_f32 v39, v100, v101
	v_cvt_pk_bf16_f32 v40, v106, v107
	v_cvt_pk_bf16_f32 v41, v102, v103
	global_store_dwordx4 v[4:5], v[38:41], off offset:3072
	s_nop 0
	v_mul_f32_e32 v1, 0x4b800000, v2
	v_cndmask_b32_e32 v1, v2, v1, vcc
	v_rsq_f32_e32 v1, v1
	v_lshl_add_u64 v[98:99], v[70:71], 0, s[22:23]
	v_mov_b32_e32 v13, v8
	v_mov_b32_e32 v15, v16
	v_mul_f32_e32 v2, 0x45800000, v1
	v_cndmask_b32_e32 v148, v1, v2, vcc
	v_pk_mul_f32 v[2:3], v[148:149], v[32:33] op_sel_hi:[0,1]
	v_pk_mul_f32 v[4:5], v[148:149], v[22:23] op_sel_hi:[0,1]
	v_pk_mul_f32 v[22:23], v[148:149], v[30:31] op_sel_hi:[0,1]
	v_pk_mul_f32 v[24:25], v[148:149], v[24:25] op_sel_hi:[0,1]
	v_pk_mul_f32 v[12:13], v[148:149], v[12:13] op_sel_hi:[0,1]
	v_pk_mul_f32 v[126:127], v[148:149], v[128:129] op_sel_hi:[0,1]
	v_pk_mul_f32 v[124:125], v[148:149], v[124:125] op_sel_hi:[0,1]
	v_pk_mul_f32 v[128:129], v[148:149], v[134:135] op_sel_hi:[0,1]
	v_pk_mul_f32 v[130:131], v[148:149], v[132:133] op_sel_hi:[0,1]
	v_pk_mul_f32 v[242:243], v[148:149], v[136:137] op_sel_hi:[0,1]
	v_pk_mul_f32 v[246:247], v[148:149], v[138:139] op_sel_hi:[0,1]
	v_pk_mul_f32 v[240:241], v[148:149], v[144:145] op_sel_hi:[0,1]
	v_pk_mul_f32 v[244:245], v[148:149], v[146:147] op_sel_hi:[0,1]
	s_waitcnt vmcnt(6)
	s_nop 1
	v_mov_b64_e32 v[38:39], v[150:151]
	v_mov_b64_e32 v[40:41], v[152:153]
	v_mov_b64_e32 v[42:43], v[154:155]
	v_mov_b64_e32 v[44:45], v[156:157]
	v_mov_b64_e32 v[46:47], v[158:159]
	v_mov_b64_e32 v[48:49], v[160:161]
	v_mov_b64_e32 v[50:51], v[162:163]
	v_mov_b64_e32 v[52:53], v[164:165]
	v_mov_b64_e32 v[54:55], v[166:167]
	v_mov_b64_e32 v[56:57], v[168:169]
	v_mov_b64_e32 v[114:115], v[170:171]
	v_mov_b64_e32 v[116:117], v[172:173]
	global_load_dwordx4 v[150:153], v[66:67], off
	global_load_dwordx4 v[154:157], v214, s[98:99]
	global_load_dwordx4 v[158:161], v[66:67], off offset:16
	global_load_dwordx4 v[162:165], v214, s[98:99] offset:16
	global_load_dwordx4 v[166:169], v214, s[100:101] offset:16
	global_load_dwordx4 v[170:173], v214, s[100:101]
	v_pk_add_f32 v[26:27], v[44:45], 1.0 op_sel_hi:[1,0]
	v_pk_mul_f32 v[4:5], v[38:39], v[4:5]
	v_pk_mul_f32 v[2:3], v[40:41], v[2:3]
	v_pk_add_f32 v[28:29], v[42:43], 1.0 op_sel_hi:[1,0]
	v_pk_mul_f32 v[24:25], v[46:47], v[24:25]
	v_pk_mul_f32 v[22:23], v[48:49], v[22:23]
	v_pk_add_f32 v[30:31], v[52:53], 1.0 op_sel_hi:[1,0]
	v_pk_add_f32 v[32:33], v[50:51], 1.0 op_sel_hi:[1,0]
	v_pk_fma_f32 v[108:109], v[26:27], v[2:3], v[56:57]
	v_pk_fma_f32 v[112:113], v[28:29], v[4:5], v[54:55]
	v_pk_fma_f32 v[110:111], v[30:31], v[22:23], v[116:117]
	v_pk_fma_f32 v[114:115], v[32:33], v[24:25], v[114:115]
	v_cvt_pk_bf16_f32 v2, v112, v113
	v_cvt_pk_bf16_f32 v3, v108, v109
	v_cvt_pk_bf16_f32 v4, v114, v115
	v_cvt_pk_bf16_f32 v5, v110, v111
	global_store_dwordx4 v[98:99], v[2:5], off
	s_nop 0
	v_mov_b32_e32 v11, v6
	v_pk_mul_f32 v[6:7], v[148:149], v[14:15] op_sel_hi:[0,1]
	v_pk_mul_f32 v[8:9], v[148:149], v[10:11] op_sel_hi:[0,1]
	v_pk_mul_f32 v[10:11], v[148:149], v[18:19] op_sel_hi:[0,1]
	s_waitcnt vmcnt(6)
; #define LAS __attribute__((address_space(3)))
; __device__ __forceinline__ unsigned pk2(float lo, float hi) { return f2bf(lo) | (f2bf(hi) << 16); }
; template <bool ZP, bool XF32, bool OUT8 = false>
; __device__ __forceinline__ void norm_phase(LAS unsigned char* lds, const void* xin, const float* gain, const float* sh, const float* sc, bf16* hout, const float* wzt, float* zout, int lane, int wave, int vcu, int G) {
;     ...
;         for (int r = 0; r < 2; ++r) { const int m = m0 + r, b = m >> 11;
;             const float rstd = rsqrtf(wave_sum(ss[r]) * (1.0f / D) + EPS);
; #pragma unroll
;             for (int j = 0; j < 4; ++j) { const int col = 512 * j + 8 * lane;
; #pragma unroll
;                 for (int q = 0; q < 2; ++q) { const f32x4 gg = *(const f32x4*)(gain + col + 4 * q), s1 = *(const f32x4*)(sc + (size_t)b * MODW + col + 4 * q), s0 = *(const f32x4*)(sh + (size_t)b * MODW + col + 4 * q);
;                     v[r][j][q] = (v[r][j][q] * rstd * gg) * (s1 + 1.0f) + s0; }
;                 if constexpr (OUT8) { *(v2u*)((unsigned char*)hout + (size_t)m * D + col) = pack8_fp8(v[r][j][0][0], v[r][j][0][1], v[r][j][0][2], v[r][j][0][3], v[r][j][1][0], v[r][j][1][1], v[r][j][1][2], v[r][j][1][3], FP8_ASCALE); }
;                 else { v4u o; o.x = pk2(v[r][j][0][0], v[r][j][0][1]); o.y = pk2(v[r][j][0][2], v[r][j][0][3]); o.z = pk2(v[r][j][1][0], v[r][j][1][1]); o.w = pk2(v[r][j][1][2], v[r][j][1][3]);
;                     *(v4u*)(hout + (size_t)m * D + col) = o; } }
;         }
;         if constexpr (ZP) {
;             float p0[16], p1[16];
; #pragma unroll
;             for (int rr = 0; rr < 16; ++rr) { p0[rr] = 0.f; p1[rr] = 0.f;
; #pragma unroll
;                 for (int j = 0; j < 4; ++j) { const f32x4 w0 = *(const LAS f32x4*)(wl + (((rr * 4 + j) * 2 + 0) * 64 + lane) * 4), w1 = *(const LAS f32x4*)(wl + (((rr * 4 + j) * 2 + 1) * 64 + lane) * 4);
; #pragma unroll
;                     for (int e = 0; e < 4; ++e) { p0[rr] += v[0][j][0][e] * w0[e] + v[0][j][1][e] * w1[e]; p1[rr] += v[1][j][0][e] * w0[e] + v[1][j][1][e] * w1[e]; } } }
	s_nop 1
	v_mov_b64_e32 v[2:3], v[174:175]
	v_mov_b64_e32 v[4:5], v[176:177]
	v_mov_b64_e32 v[22:23], v[178:179]
	v_mov_b64_e32 v[24:25], v[180:181]
	v_mov_b64_e32 v[26:27], v[182:183]
	v_mov_b64_e32 v[28:29], v[184:185]
	v_mov_b64_e32 v[30:31], v[186:187]
	v_mov_b64_e32 v[32:33], v[188:189]
	v_mov_b64_e32 v[34:35], v[190:191]
	v_mov_b64_e32 v[36:37], v[192:193]
	v_mov_b64_e32 v[38:39], v[194:195]
	v_mov_b64_e32 v[40:41], v[196:197]
	global_load_dwordx4 v[174:177], v[68:69], off offset:16
	global_load_dwordx4 v[178:181], v[68:69], off
	global_load_dwordx4 v[182:185], v215, s[98:99] offset:16
	global_load_dwordx4 v[186:189], v215, s[98:99]
	global_load_dwordx4 v[190:193], v215, s[100:101] offset:16
	global_load_dwordx4 v[194:197], v215, s[100:101]
	v_pk_mul_f32 v[2:3], v[2:3], v[8:9]
	v_pk_mul_f32 v[4:5], v[4:5], v[6:7]
	v_pk_add_f32 v[6:7], v[24:25], 1.0 op_sel_hi:[1,0]
	v_pk_add_f32 v[8:9], v[22:23], 1.0 op_sel_hi:[1,0]
	v_pk_mul_f32 v[12:13], v[26:27], v[12:13]
	v_pk_mul_f32 v[10:11], v[28:29], v[10:11]
	v_pk_add_f32 v[14:15], v[32:33], 1.0 op_sel_hi:[1,0]
	v_pk_add_f32 v[16:17], v[30:31], 1.0 op_sel_hi:[1,0]
	v_pk_fma_f32 v[116:117], v[6:7], v[4:5], v[36:37]
	v_pk_fma_f32 v[120:121], v[8:9], v[2:3], v[34:35]
	v_pk_fma_f32 v[118:119], v[14:15], v[10:11], v[40:41]
	v_pk_fma_f32 v[122:123], v[16:17], v[12:13], v[38:39]
	v_cvt_pk_bf16_f32 v2, v120, v121
	v_cvt_pk_bf16_f32 v3, v116, v117
	v_cvt_pk_bf16_f32 v4, v122, v123
	v_cvt_pk_bf16_f32 v5, v118, v119
	global_store_dwordx4 v[98:99], v[2:5], off offset:1024
	s_nop 0
	ds_read_b128 v[18:21], v73
	ds_read_b128 v[22:25], v73 offset:1024
	ds_read_b128 v[26:29], v73 offset:2048
	ds_read_b128 v[30:33], v73 offset:3072
	ds_read_b128 v[38:41], v73 offset:4096
	ds_read_b128 v[42:45], v73 offset:5120
	ds_read_b128 v[34:37], v73 offset:6144
	ds_read_b128 v[46:49], v73 offset:7168
	ds_read_b128 v[232:235], v73 offset:8192
	ds_read_b128 v[236:239], v73 offset:9216
	ds_read_b128 v[50:53], v73 offset:10240
	ds_read_b128 v[54:57], v73 offset:11264
	s_waitcnt lgkmcnt(6)
	v_mul_f32_e32 v223, v96, v42
	v_fmac_f32_e32 v223, v94, v38
	v_mul_f32_e32 v1, v82, v22
	v_mul_f32_e32 v132, v83, v23
	v_fmac_f32_e32 v1, v78, v18
	v_mul_f32_e32 v133, v76, v24
	s_waitcnt lgkmcnt(2)
	v_mul_f32_e32 v135, v82, v236
	v_fmac_f32_e32 v132, v79, v19
	v_add_f32_e32 v1, 0, v1
	v_mul_f32_e32 v134, v77, v25
	v_mul_f32_e32 v136, v83, v237
	v_fmac_f32_e32 v133, v74, v20
	v_fmac_f32_e32 v135, v78, v232
	v_add_f32_e32 v1, v132, v1
	v_mul_f32_e32 v137, v76, v238
	v_fmac_f32_e32 v134, v75, v21
	v_fmac_f32_e32 v136, v79, v233
	v_add_f32_e32 v135, 0, v135
	v_add_f32_e32 v1, v133, v1
	v_mul_f32_e32 v133, v88, v30
	v_mul_f32_e32 v138, v77, v239
	v_fmac_f32_e32 v137, v74, v234
	v_add_f32_e32 v132, v136, v135
	v_add_f32_e32 v1, v134, v1
	v_mul_f32_e32 v134, v89, v31
	v_fmac_f32_e32 v133, v84, v26
	v_fmac_f32_e32 v138, v75, v235
	v_add_f32_e32 v132, v137, v132
	v_mul_f32_e32 v135, v86, v32
	s_waitcnt lgkmcnt(0)
	v_mul_f32_e32 v137, v88, v54
	v_fmac_f32_e32 v134, v85, v27
	v_add_f32_e32 v1, v133, v1
	v_add_f32_e32 v132, v138, v132
	v_mul_f32_e32 v136, v87, v33
	v_mul_f32_e32 v138, v89, v55
	v_fmac_f32_e32 v135, v80, v28
	v_fmac_f32_e32 v137, v84, v50
	v_add_f32_e32 v1, v134, v1
	v_fmac_f32_e32 v136, v81, v29
	v_fmac_f32_e32 v138, v85, v51
	v_add_f32_e32 v132, v137, v132
	v_add_f32_e32 v1, v135, v1
	v_add_f32_e32 v148, v138, v132
	v_add_f32_e32 v1, v136, v1
	v_add_f32_e32 v1, v223, v1
	s_waitcnt vmcnt(6)
	s_nop 1
	v_mov_b64_e32 v[10:11], v[150:151]
	v_mov_b64_e32 v[12:13], v[152:153]
	v_mov_b64_e32 v[14:15], v[154:155]
	v_mov_b64_e32 v[16:17], v[156:157]
	v_mov_b64_e32 v[6:7], v[158:159]
	v_mov_b64_e32 v[8:9], v[160:161]
	v_mov_b64_e32 v[2:3], v[162:163]
	v_mov_b64_e32 v[4:5], v[164:165]
	v_mov_b64_e32 v[224:225], v[166:167]
	v_mov_b64_e32 v[226:227], v[168:169]
	v_mov_b64_e32 v[228:229], v[170:171]
	v_mov_b64_e32 v[230:231], v[172:173]
	v_pk_mul_f32 v[10:11], v[124:125], v[10:11]
	v_pk_mul_f32 v[12:13], v[126:127], v[12:13]
	v_pk_add_f32 v[16:17], v[16:17], 1.0 op_sel_hi:[1,0]
	v_pk_add_f32 v[14:15], v[14:15], 1.0 op_sel_hi:[1,0]
	v_pk_mul_f32 v[6:7], v[130:131], v[6:7]
	v_pk_mul_f32 v[124:125], v[128:129], v[8:9]
	v_pk_add_f32 v[4:5], v[4:5], 1.0 op_sel_hi:[1,0]
	v_pk_add_f32 v[2:3], v[2:3], 1.0 op_sel_hi:[1,0]
	v_pk_fma_f32 v[8:9], v[12:13], v[16:17], v[230:231]
	v_pk_fma_f32 v[12:13], v[10:11], v[14:15], v[228:229]
	v_pk_fma_f32 v[10:11], v[124:125], v[4:5], v[226:227]
	v_pk_fma_f32 v[14:15], v[6:7], v[2:3], v[224:225]
	v_cvt_pk_bf16_f32 v2, v12, v13
	v_cvt_pk_bf16_f32 v3, v8, v9
	v_cvt_pk_bf16_f32 v4, v14, v15
	v_cvt_pk_bf16_f32 v5, v10, v11
	global_store_dwordx4 v[98:99], v[2:5], off offset:2048
	s_nop 1
	v_mul_f32_e32 v2, v97, v43
	v_mul_f32_e32 v3, v92, v44
	v_fmac_f32_e32 v2, v95, v39
	v_mul_f32_e32 v4, v93, v45
	v_fmac_f32_e32 v3, v90, v40
	v_add_f32_e32 v1, v2, v1
	v_fmac_f32_e32 v4, v91, v41
	v_add_f32_e32 v1, v3, v1
	v_mul_f32_e32 v2, v106, v46
	v_add_f32_e32 v1, v4, v1
	v_mul_f32_e32 v3, v107, v47
	v_fmac_f32_e32 v2, v104, v34
	v_mul_f32_e32 v4, v102, v48
	v_fmac_f32_e32 v3, v105, v35
	v_add_f32_e32 v1, v2, v1
	v_mul_f32_e32 v5, v103, v49
	v_fmac_f32_e32 v4, v100, v36
	v_add_f32_e32 v1, v3, v1
	v_fmac_f32_e32 v5, v101, v37
	v_add_f32_e32 v1, v4, v1
	v_add_f32_e32 v5, v5, v1
	v_mul_f32_e32 v1, v114, v22
	v_mul_f32_e32 v2, v115, v23
	v_fmac_f32_e32 v1, v112, v18
	v_mul_f32_e32 v3, v110, v24
	v_mul_f32_e32 v6, v114, v236
	v_fmac_f32_e32 v2, v113, v19
	v_add_f32_e32 v1, 0, v1
	v_mul_f32_e32 v4, v111, v25
	v_mul_f32_e32 v7, v115, v237
	v_fmac_f32_e32 v3, v108, v20
	v_fmac_f32_e32 v6, v112, v232
	v_add_f32_e32 v1, v2, v1
	v_mul_f32_e32 v16, v110, v238
	v_fmac_f32_e32 v4, v109, v21
	v_fmac_f32_e32 v7, v113, v233
	v_add_f32_e32 v6, 0, v6
	v_add_f32_e32 v1, v3, v1
	v_mul_f32_e32 v3, v122, v30
	v_mul_f32_e32 v17, v111, v239
	v_fmac_f32_e32 v16, v108, v234
	v_add_f32_e32 v2, v7, v6
	v_add_f32_e32 v1, v4, v1
	v_mul_f32_e32 v4, v123, v31
	v_fmac_f32_e32 v3, v120, v26
	v_fmac_f32_e32 v17, v109, v235
	v_add_f32_e32 v2, v16, v2
	v_mul_f32_e32 v6, v118, v32
	v_mul_f32_e32 v16, v122, v54
	v_fmac_f32_e32 v4, v121, v27
	v_add_f32_e32 v1, v3, v1
	v_add_f32_e32 v2, v17, v2
	v_mul_f32_e32 v7, v119, v33
	v_fmac_f32_e32 v6, v116, v28
	v_fmac_f32_e32 v16, v120, v50
	v_add_f32_e32 v1, v4, v1
	v_fmac_f32_e32 v7, v117, v29
	v_add_f32_e32 v28, v16, v2
	v_add_f32_e32 v1, v6, v1
	v_mul_f32_e32 v2, v14, v42
	v_add_f32_e32 v1, v7, v1
	v_mul_f32_e32 v3, v15, v43
	v_fmac_f32_e32 v2, v12, v38
	v_mul_f32_e32 v4, v10, v44
	v_fmac_f32_e32 v3, v13, v39
	v_add_f32_e32 v1, v2, v1
	v_mul_f32_e32 v6, v11, v45
	v_fmac_f32_e32 v4, v8, v40
	v_add_f32_e32 v1, v3, v1
	v_fmac_f32_e32 v6, v9, v41
	v_add_f32_e32 v1, v4, v1
	v_add_f32_e32 v4, v6, v1
	v_mul_f32_e32 v30, v123, v55
	v_fmac_f32_e32 v30, v121, v51
	v_mul_f32_e32 v33, v87, v57
	s_waitcnt vmcnt(0)
; #define LAS __attribute__((address_space(3)))
; __device__ __forceinline__ unsigned pk2(float lo, float hi) { return f2bf(lo) | (f2bf(hi) << 16); }
; template <bool ZP, bool XF32, bool OUT8 = false>
; __device__ __forceinline__ void norm_phase(LAS unsigned char* lds, const void* xin, const float* gain, const float* sh, const float* sc, bf16* hout, const float* wzt, float* zout, int lane, int wave, int vcu, int G) {
;     ...
;             for (int j = 0; j < 4; ++j) { const int col = 512 * j + 8 * lane;
; #pragma unroll
;                 for (int q = 0; q < 2; ++q) { const f32x4 gg = *(const f32x4*)(gain + col + 4 * q), s1 = *(const f32x4*)(sc + (size_t)b * MODW + col + 4 * q), s0 = *(const f32x4*)(sh + (size_t)b * MODW + col + 4 * q);
;                     v[r][j][q] = (v[r][j][q] * rstd * gg) * (s1 + 1.0f) + s0; }
;                 if constexpr (OUT8) { *(v2u*)((unsigned char*)hout + (size_t)m * D + col) = pack8_fp8(v[r][j][0][0], v[r][j][0][1], v[r][j][0][2], v[r][j][0][3], v[r][j][1][0], v[r][j][1][1], v[r][j][1][2], v[r][j][1][3], FP8_ASCALE); }
;                 else { v4u o; o.x = pk2(v[r][j][0][0], v[r][j][0][1]); o.y = pk2(v[r][j][0][2], v[r][j][0][3]); o.z = pk2(v[r][j][1][0], v[r][j][1][1]); o.w = pk2(v[r][j][1][2], v[r][j][1][3]);
;                     *(v4u*)(hout + (size_t)m * D + col) = o; } }
;         }
;         if constexpr (ZP) {
;             float p0[16], p1[16];
; #pragma unroll
;             for (int rr = 0; rr < 16; ++rr) { p0[rr] = 0.f; p1[rr] = 0.f;
; #pragma unroll
;                 for (int j = 0; j < 4; ++j) { const f32x4 w0 = *(const LAS f32x4*)(wl + (((rr * 4 + j) * 2 + 0) * 64 + lane) * 4), w1 = *(const LAS f32x4*)(wl + (((rr * 4 + j) * 2 + 1) * 64 + lane) * 4);
; #pragma unroll
;                     for (int e = 0; e < 4; ++e) { p0[rr] += v[0][j][0][e] * w0[e] + v[0][j][1][e] * w1[e]; p1[rr] += v[1][j][0][e] * w0[e] + v[1][j][1][e] * w1[e]; } } }
	s_nop 1
	v_mov_b64_e32 v[124:125], v[174:175]
	v_mov_b64_e32 v[126:127], v[176:177]
	v_mov_b64_e32 v[128:129], v[178:179]
	v_mov_b64_e32 v[130:131], v[180:181]
	v_mov_b64_e32 v[132:133], v[182:183]
	v_mov_b64_e32 v[134:135], v[184:185]
	v_mov_b64_e32 v[136:137], v[186:187]
	v_mov_b64_e32 v[138:139], v[188:189]
	v_mov_b64_e32 v[140:141], v[190:191]
	v_mov_b64_e32 v[142:143], v[192:193]
	v_mov_b64_e32 v[144:145], v[194:195]
	v_mov_b64_e32 v[146:147], v[196:197]
	v_add_u32_e32 v150, 0x10400, v73
	v_add_u32_e32 v151, 0x10800, v73
	v_add_u32_e32 v152, 0x10c00, v73
	v_add_u32_e32 v153, 0x11000, v73
	v_add_u32_e32 v154, 0x11400, v73
	v_add_u32_e32 v155, 0x11800, v73
	v_add_u32_e32 v156, 0x11c00, v73
	v_add_u32_e32 v157, 0x12000, v73
	v_add_u32_e32 v158, 0x12400, v73
	v_add_u32_e32 v159, 0x12800, v73
	v_add_u32_e32 v160, 0x12c00, v73
	v_add_u32_e32 v161, 0x13000, v73
	v_add_u32_e32 v162, 0x13400, v73
	v_add_u32_e32 v163, 0x13800, v73
	v_add_u32_e32 v164, 0x13c00, v73
	v_add_u32_e32 v165, 0x14000, v73
	v_add_u32_e32 v166, 0x14400, v73
	v_add_u32_e32 v167, 0x14800, v73
	v_add_u32_e32 v168, 0x14c00, v73
	v_add_u32_e32 v169, 0x15000, v73
	v_add_u32_e32 v170, 0x15400, v73
	v_add_u32_e32 v171, 0x15800, v73
	v_add_u32_e32 v172, 0x15c00, v73
	v_add_u32_e32 v173, 0x16000, v73
	v_add_u32_e32 v174, 0x16400, v73
	v_add_u32_e32 v175, 0x16800, v73
	v_add_u32_e32 v176, 0x16c00, v73
	v_add_u32_e32 v177, 0x17000, v73
	v_add_u32_e32 v178, 0x17400, v73
	v_add_u32_e32 v179, 0x17800, v73
	v_add_u32_e32 v180, 0x17c00, v73
	v_add_u32_e32 v181, 0x18000, v73
	v_add_u32_e32 v182, 0x18400, v73
	v_add_u32_e32 v183, 0x18800, v73
	v_add_u32_e32 v184, 0x18c00, v73
	v_add_u32_e32 v185, 0x19000, v73
	v_add_u32_e32 v186, 0x19400, v73
	v_add_u32_e32 v187, 0x19800, v73
	v_add_u32_e32 v188, 0x19c00, v73
	v_add_u32_e32 v189, 0x1a000, v73
	v_add_u32_e32 v190, 0x1a400, v73
	v_add_u32_e32 v191, 0x1a800, v73
	v_add_u32_e32 v192, 0x1ac00, v73
	v_add_u32_e32 v193, 0x1b000, v73
	v_add_u32_e32 v194, 0x1b400, v73
	v_add_u32_e32 v195, 0x1b800, v73
	v_add_u32_e32 v196, 0x1bc00, v73
	v_add_u32_e32 v197, 0x1c000, v73
	v_pk_mul_f32 v[20:21], v[246:247], v[124:125]
	v_pk_mul_f32 v[6:7], v[240:241], v[130:131]
	v_pk_add_f32 v[26:27], v[132:133], 1.0 op_sel_hi:[1,0]
	v_pk_add_f32 v[16:17], v[138:139], 1.0 op_sel_hi:[1,0]
	v_pk_mul_f32 v[22:23], v[244:245], v[126:127]
	v_pk_add_f32 v[24:25], v[134:135], 1.0 op_sel_hi:[1,0]
	v_pk_fma_f32 v[20:21], v[20:21], v[26:27], v[140:141]
	v_pk_mul_f32 v[2:3], v[242:243], v[128:129]
	v_pk_add_f32 v[18:19], v[136:137], 1.0 op_sel_hi:[1,0]
	v_pk_fma_f32 v[16:17], v[6:7], v[16:17], v[146:147]
	v_pk_fma_f32 v[6:7], v[22:23], v[24:25], v[142:143]
	v_pk_fma_f32 v[18:19], v[2:3], v[18:19], v[144:145]
	v_mul_f32_e32 v26, v20, v46
	v_fmac_f32_e32 v26, v18, v34
	v_mul_f32_e32 v27, v21, v47
	v_add_f32_e32 v26, v26, v4
	v_cvt_pk_bf16_f32 v4, v20, v21
	v_mul_f32_e32 v24, v86, v56
	v_mul_f32_e32 v29, v6, v48
	v_fmac_f32_e32 v27, v19, v35
	v_fmac_f32_e32 v24, v80, v52
	v_mul_f32_e32 v31, v7, v49
	v_fmac_f32_e32 v29, v16, v36
	v_cvt_pk_bf16_f32 v2, v18, v19
	v_cvt_pk_bf16_f32 v3, v16, v17
	v_add_f32_e32 v22, v27, v26
	v_add_f32_e32 v32, v24, v148
	v_mul_f32_e32 v24, v118, v56
	v_fmac_f32_e32 v31, v17, v37
	v_add_f32_e32 v22, v29, v22
	v_add_f32_e32 v23, v30, v28
	v_fmac_f32_e32 v24, v116, v52
	v_add_f32_e32 v22, v31, v22
	v_add_f32_e32 v23, v24, v23
	ds_read_b128 v[24:27], v73 offset:12288
	ds_read_b128 v[28:31], v73 offset:13312
	v_fmac_f32_e32 v33, v81, v53
	v_add_f32_e32 v32, v33, v32
	v_mul_f32_e32 v33, v119, v57
	v_fmac_f32_e32 v33, v117, v53
	v_add_f32_e32 v23, v33, v23
	s_waitcnt lgkmcnt(0)
	v_mul_f32_e32 v33, v96, v28
	v_mul_f32_e32 v28, v14, v28
	v_fmac_f32_e32 v28, v12, v24
	v_fmac_f32_e32 v33, v94, v24
	v_add_f32_e32 v23, v28, v23
	v_mul_f32_e32 v24, v97, v29
	v_mul_f32_e32 v28, v15, v29
	v_add_f32_e32 v32, v33, v32
	v_fmac_f32_e32 v24, v95, v25
	v_fmac_f32_e32 v28, v13, v25
	v_mul_f32_e32 v25, v92, v30
	v_add_f32_e32 v24, v24, v32
	v_fmac_f32_e32 v25, v90, v26
	v_add_f32_e32 v24, v25, v24
	v_mul_f32_e32 v25, v10, v30
	v_add_f32_e32 v23, v28, v23
	v_fmac_f32_e32 v25, v8, v26
	ds_read_b128 v[32:35], v73 offset:14336
	ds_read_b128 v[36:39], v73 offset:15360
	v_add_f32_e32 v23, v25, v23
	v_mul_f32_e32 v25, v93, v31
	v_fmac_f32_e32 v25, v91, v27
	v_add_f32_e32 v24, v25, v24
	v_mul_f32_e32 v25, v11, v31
	v_fmac_f32_e32 v25, v9, v27
	v_add_f32_e32 v23, v25, v23
	s_waitcnt lgkmcnt(0)
	v_mul_f32_e32 v25, v106, v36
	v_fmac_f32_e32 v25, v104, v32
	v_add_f32_e32 v24, v25, v24
	v_mul_f32_e32 v25, v20, v36
	v_fmac_f32_e32 v25, v18, v32
	v_add_f32_e32 v23, v25, v23
	v_mul_f32_e32 v25, v107, v37
	v_fmac_f32_e32 v25, v105, v33
	v_add_f32_e32 v24, v25, v24
	v_mul_f32_e32 v25, v21, v37
	v_fmac_f32_e32 v25, v19, v33
	v_add_f32_e32 v23, v25, v23
	v_mul_f32_e32 v25, v102, v38
	v_fmac_f32_e32 v25, v100, v34
	v_add_f32_e32 v24, v25, v24
	v_mul_f32_e32 v25, v6, v38
	v_fmac_f32_e32 v25, v16, v34
	ds_read_b128 v[26:29], v73 offset:16384
	ds_read_b128 v[30:33], v73 offset:17408
	v_add_f32_e32 v23, v25, v23
	v_mul_f32_e32 v25, v103, v39
	v_fmac_f32_e32 v25, v101, v35
	v_add_f32_e32 v24, v25, v24
	v_mul_f32_e32 v25, v7, v39
	v_fmac_f32_e32 v25, v17, v35
	v_add_f32_e32 v23, v25, v23
	s_waitcnt lgkmcnt(0)
; #define LAS __attribute__((address_space(3)))
; template <bool ZP, bool XF32, bool OUT8 = false>
; __device__ __forceinline__ void norm_phase(LAS unsigned char* lds, const void* xin, const float* gain, const float* sh, const float* sc, bf16* hout, const float* wzt, float* zout, int lane, int wave, int vcu, int G) {
;     ...
;         if constexpr (ZP) {
;             float p0[16], p1[16];
; #pragma unroll
;             for (int rr = 0; rr < 16; ++rr) { p0[rr] = 0.f; p1[rr] = 0.f;
; #pragma unroll
;                 for (int j = 0; j < 4; ++j) { const f32x4 w0 = *(const LAS f32x4*)(wl + (((rr * 4 + j) * 2 + 0) * 64 + lane) * 4), w1 = *(const LAS f32x4*)(wl + (((rr * 4 + j) * 2 + 1) * 64 + lane) * 4);
; #pragma unroll
;                     for (int e = 0; e < 4; ++e) { p0[rr] += v[0][j][0][e] * w0[e] + v[0][j][1][e] * w1[e]; p1[rr] += v[1][j][0][e] * w0[e] + v[1][j][1][e] * w1[e]; } } }
	v_mul_f32_e32 v25, v82, v30
	v_mul_f32_e32 v30, v114, v30
	v_fmac_f32_e32 v30, v112, v26
	v_fmac_f32_e32 v25, v78, v26
	v_add_f32_e32 v26, 0, v30
	v_mul_f32_e32 v30, v83, v31
	v_add_f32_e32 v25, 0, v25
	v_fmac_f32_e32 v30, v79, v27
	v_add_f32_e32 v25, v30, v25
	v_mul_f32_e32 v30, v115, v31
	v_fmac_f32_e32 v30, v113, v27
	v_mul_f32_e32 v27, v76, v32
	v_fmac_f32_e32 v27, v74, v28
	v_add_f32_e32 v25, v27, v25
	v_mul_f32_e32 v27, v110, v32
	v_add_f32_e32 v26, v30, v26
	v_fmac_f32_e32 v27, v108, v28
	ds_read_b128 v[34:37], v73 offset:18432
	ds_read_b128 v[38:41], v73 offset:19456
	v_add_f32_e32 v26, v27, v26
	v_mul_f32_e32 v27, v77, v33
	v_fmac_f32_e32 v27, v75, v29
	v_add_f32_e32 v25, v27, v25
	v_mul_f32_e32 v27, v111, v33
	v_fmac_f32_e32 v27, v109, v29
	v_add_f32_e32 v26, v27, v26
	s_waitcnt lgkmcnt(0)
	v_mul_f32_e32 v27, v88, v38
	v_fmac_f32_e32 v27, v84, v34
	v_add_f32_e32 v25, v27, v25
	v_mul_f32_e32 v27, v122, v38
	v_fmac_f32_e32 v27, v120, v34
	v_add_f32_e32 v26, v27, v26
	v_mul_f32_e32 v27, v89, v39
	v_fmac_f32_e32 v27, v85, v35
	v_add_f32_e32 v25, v27, v25
	v_mul_f32_e32 v27, v123, v39
	v_fmac_f32_e32 v27, v121, v35
	v_add_f32_e32 v26, v27, v26
	v_mul_f32_e32 v27, v86, v40
	v_fmac_f32_e32 v27, v80, v36
	v_add_f32_e32 v25, v27, v25
	v_mul_f32_e32 v27, v118, v40
	v_fmac_f32_e32 v27, v116, v36
	v_add_f32_e32 v34, v27, v26
	ds_read_b128 v[26:29], v73 offset:20480
	ds_read_b128 v[30:33], v73 offset:21504
	v_mul_f32_e32 v35, v87, v41
	v_fmac_f32_e32 v35, v81, v37
	v_add_f32_e32 v25, v35, v25
	v_mul_f32_e32 v35, v119, v41
	v_fmac_f32_e32 v35, v117, v37
	v_add_f32_e32 v34, v35, v34
	s_waitcnt lgkmcnt(0)
	v_mul_f32_e32 v35, v96, v30
	v_mul_f32_e32 v30, v14, v30
	v_fmac_f32_e32 v30, v12, v26
	v_fmac_f32_e32 v35, v94, v26
	v_add_f32_e32 v26, v30, v34
	v_mul_f32_e32 v30, v97, v31
	v_add_f32_e32 v25, v35, v25
	v_fmac_f32_e32 v30, v95, v27
	v_add_f32_e32 v25, v30, v25
	v_mul_f32_e32 v30, v15, v31
	v_fmac_f32_e32 v30, v13, v27
	v_mul_f32_e32 v27, v92, v32
	v_fmac_f32_e32 v27, v90, v28
	v_add_f32_e32 v25, v27, v25
	v_mul_f32_e32 v27, v10, v32
	v_add_f32_e32 v26, v30, v26
	v_fmac_f32_e32 v27, v8, v28
	ds_read_b128 v[34:37], v73 offset:22528
	ds_read_b128 v[38:41], v73 offset:23552
	v_add_f32_e32 v26, v27, v26
	v_mul_f32_e32 v27, v93, v33
	v_fmac_f32_e32 v27, v91, v29
	v_add_f32_e32 v25, v27, v25
	v_mul_f32_e32 v27, v11, v33
	v_fmac_f32_e32 v27, v9, v29
	v_add_f32_e32 v26, v27, v26
	s_waitcnt lgkmcnt(0)
	v_mul_f32_e32 v27, v106, v38
	v_fmac_f32_e32 v27, v104, v34
	v_add_f32_e32 v25, v27, v25
	v_mul_f32_e32 v27, v20, v38
	v_fmac_f32_e32 v27, v18, v34
	v_add_f32_e32 v26, v27, v26
	v_mul_f32_e32 v27, v107, v39
	v_fmac_f32_e32 v27, v105, v35
	v_add_f32_e32 v25, v27, v25
	v_mul_f32_e32 v27, v21, v39
	v_fmac_f32_e32 v27, v19, v35
	v_add_f32_e32 v26, v27, v26
	v_mul_f32_e32 v27, v102, v40
	v_fmac_f32_e32 v27, v100, v36
	v_add_f32_e32 v25, v27, v25
	v_mul_f32_e32 v27, v6, v40
	v_fmac_f32_e32 v27, v16, v36
	ds_read_b128 v[28:31], v73 offset:24576
	ds_read_b128 v[32:35], v73 offset:25600
	v_add_f32_e32 v27, v27, v26
	v_mul_f32_e32 v26, v103, v41
	v_fmac_f32_e32 v26, v101, v37
	v_add_f32_e32 v26, v26, v25
	v_mul_f32_e32 v25, v7, v41
	v_fmac_f32_e32 v25, v17, v37
	v_add_f32_e32 v25, v25, v27
	s_waitcnt lgkmcnt(0)
	v_mul_f32_e32 v27, v82, v32
	v_mul_f32_e32 v32, v114, v32
	v_fmac_f32_e32 v32, v112, v28
	v_fmac_f32_e32 v27, v78, v28
	v_add_f32_e32 v28, 0, v32
	v_mul_f32_e32 v32, v83, v33
	v_add_f32_e32 v27, 0, v27
	v_fmac_f32_e32 v32, v79, v29
	v_add_f32_e32 v27, v32, v27
	v_mul_f32_e32 v32, v115, v33
	v_fmac_f32_e32 v32, v113, v29
	v_mul_f32_e32 v29, v76, v34
	v_fmac_f32_e32 v29, v74, v30
	v_add_f32_e32 v27, v29, v27
	v_mul_f32_e32 v29, v110, v34
	v_add_f32_e32 v28, v32, v28
	v_fmac_f32_e32 v29, v108, v30
	ds_read_b128 v[36:39], v73 offset:26624
	ds_read_b128 v[40:43], v73 offset:27648
	v_add_f32_e32 v28, v29, v28
	v_mul_f32_e32 v29, v77, v35
	v_fmac_f32_e32 v29, v75, v31
	v_add_f32_e32 v27, v29, v27
	v_mul_f32_e32 v29, v111, v35
	v_fmac_f32_e32 v29, v109, v31
	v_add_f32_e32 v28, v29, v28
	s_waitcnt lgkmcnt(0)
	v_mul_f32_e32 v29, v88, v40
	v_fmac_f32_e32 v29, v84, v36
	v_add_f32_e32 v27, v29, v27
	v_mul_f32_e32 v29, v122, v40
	v_fmac_f32_e32 v29, v120, v36
	v_add_f32_e32 v28, v29, v28
	v_mul_f32_e32 v29, v89, v41
	v_fmac_f32_e32 v29, v85, v37
	v_add_f32_e32 v27, v29, v27
	v_mul_f32_e32 v29, v123, v41
	v_fmac_f32_e32 v29, v121, v37
	v_add_f32_e32 v28, v29, v28
	v_mul_f32_e32 v29, v86, v42
	v_fmac_f32_e32 v29, v80, v38
	v_add_f32_e32 v27, v29, v27
	v_mul_f32_e32 v29, v118, v42
	v_fmac_f32_e32 v29, v116, v38
	v_add_f32_e32 v36, v29, v28
	ds_read_b128 v[28:31], v73 offset:28672
	ds_read_b128 v[32:35], v73 offset:29696
	v_mul_f32_e32 v37, v87, v43
	v_fmac_f32_e32 v37, v81, v39
	v_add_f32_e32 v27, v37, v27
	v_mul_f32_e32 v37, v119, v43
	v_fmac_f32_e32 v37, v117, v39
	v_add_f32_e32 v36, v37, v36
	s_waitcnt lgkmcnt(0)
	v_mul_f32_e32 v37, v96, v32
	v_mul_f32_e32 v32, v14, v32
	v_fmac_f32_e32 v32, v12, v28
	v_fmac_f32_e32 v37, v94, v28
	v_add_f32_e32 v28, v32, v36
	v_mul_f32_e32 v32, v97, v33
	v_add_f32_e32 v27, v37, v27
	v_fmac_f32_e32 v32, v95, v29
	v_add_f32_e32 v27, v32, v27
	v_mul_f32_e32 v32, v15, v33
	v_fmac_f32_e32 v32, v13, v29
	v_mul_f32_e32 v29, v92, v34
	v_fmac_f32_e32 v29, v90, v30
	v_add_f32_e32 v27, v29, v27
	v_mul_f32_e32 v29, v10, v34
	v_add_f32_e32 v28, v32, v28
	v_fmac_f32_e32 v29, v8, v30
	ds_read_b128 v[36:39], v73 offset:30720
	ds_read_b128 v[40:43], v73 offset:31744
	v_add_f32_e32 v28, v29, v28
	v_mul_f32_e32 v29, v93, v35
	v_fmac_f32_e32 v29, v91, v31
	v_add_f32_e32 v27, v29, v27
	v_mul_f32_e32 v29, v11, v35
	v_fmac_f32_e32 v29, v9, v31
	v_add_f32_e32 v28, v29, v28
	s_waitcnt lgkmcnt(0)
; #define LAS __attribute__((address_space(3)))
; template <bool ZP, bool XF32, bool OUT8 = false>
; __device__ __forceinline__ void norm_phase(LAS unsigned char* lds, const void* xin, const float* gain, const float* sh, const float* sc, bf16* hout, const float* wzt, float* zout, int lane, int wave, int vcu, int G) {
;     ...
;         if constexpr (ZP) {
;             float p0[16], p1[16];
; #pragma unroll
;             for (int rr = 0; rr < 16; ++rr) { p0[rr] = 0.f; p1[rr] = 0.f;
; #pragma unroll
;                 for (int j = 0; j < 4; ++j) { const f32x4 w0 = *(const LAS f32x4*)(wl + (((rr * 4 + j) * 2 + 0) * 64 + lane) * 4), w1 = *(const LAS f32x4*)(wl + (((rr * 4 + j) * 2 + 1) * 64 + lane) * 4);
; #pragma unroll
;                     for (int e = 0; e < 4; ++e) { p0[rr] += v[0][j][0][e] * w0[e] + v[0][j][1][e] * w1[e]; p1[rr] += v[1][j][0][e] * w0[e] + v[1][j][1][e] * w1[e]; } } }
	v_mul_f32_e32 v29, v106, v40
	v_fmac_f32_e32 v29, v104, v36
	v_add_f32_e32 v27, v29, v27
	v_mul_f32_e32 v29, v20, v40
	v_fmac_f32_e32 v29, v18, v36
	v_add_f32_e32 v28, v29, v28
	v_mul_f32_e32 v29, v107, v41
	v_fmac_f32_e32 v29, v105, v37
	v_add_f32_e32 v27, v29, v27
	v_mul_f32_e32 v29, v21, v41
	v_fmac_f32_e32 v29, v19, v37
	v_add_f32_e32 v28, v29, v28
	v_mul_f32_e32 v29, v102, v42
	v_fmac_f32_e32 v29, v100, v38
	v_add_f32_e32 v27, v29, v27
	v_mul_f32_e32 v29, v6, v42
	v_fmac_f32_e32 v29, v16, v38
	ds_read_b128 v[30:33], v73 offset:32768
	ds_read_b128 v[34:37], v73 offset:33792
	v_add_f32_e32 v29, v29, v28
	v_mul_f32_e32 v28, v103, v43
	v_fmac_f32_e32 v28, v101, v39
	v_add_f32_e32 v28, v28, v27
	v_mul_f32_e32 v27, v7, v43
	v_fmac_f32_e32 v27, v17, v39
	v_add_f32_e32 v27, v27, v29
	s_waitcnt lgkmcnt(0)
	v_mul_f32_e32 v29, v82, v34
	v_mul_f32_e32 v34, v114, v34
	v_fmac_f32_e32 v34, v112, v30
	v_fmac_f32_e32 v29, v78, v30
	v_add_f32_e32 v30, 0, v34
	v_mul_f32_e32 v34, v83, v35
	v_add_f32_e32 v29, 0, v29
	v_fmac_f32_e32 v34, v79, v31
	v_add_f32_e32 v29, v34, v29
	v_mul_f32_e32 v34, v115, v35
	v_fmac_f32_e32 v34, v113, v31
	v_mul_f32_e32 v31, v76, v36
	v_fmac_f32_e32 v31, v74, v32
	v_add_f32_e32 v29, v31, v29
	v_mul_f32_e32 v31, v110, v36
	v_add_f32_e32 v30, v34, v30
	v_fmac_f32_e32 v31, v108, v32
	ds_read_b128 v[38:41], v73 offset:34816
	ds_read_b128 v[42:45], v73 offset:35840
	v_add_f32_e32 v30, v31, v30
	v_mul_f32_e32 v31, v77, v37
	v_fmac_f32_e32 v31, v75, v33
	v_add_f32_e32 v29, v31, v29
	v_mul_f32_e32 v31, v111, v37
	v_fmac_f32_e32 v31, v109, v33
	v_add_f32_e32 v30, v31, v30
	s_waitcnt lgkmcnt(0)
	v_mul_f32_e32 v31, v88, v42
	v_fmac_f32_e32 v31, v84, v38
	v_add_f32_e32 v29, v31, v29
	v_mul_f32_e32 v31, v122, v42
	v_fmac_f32_e32 v31, v120, v38
	v_add_f32_e32 v30, v31, v30
	v_mul_f32_e32 v31, v89, v43
	v_fmac_f32_e32 v31, v85, v39
	v_add_f32_e32 v29, v31, v29
	v_mul_f32_e32 v31, v123, v43
	v_fmac_f32_e32 v31, v121, v39
	v_add_f32_e32 v30, v31, v30
	v_mul_f32_e32 v31, v86, v44
	v_fmac_f32_e32 v31, v80, v40
	v_add_f32_e32 v29, v31, v29
	v_mul_f32_e32 v31, v118, v44
	v_fmac_f32_e32 v31, v116, v40
	v_add_f32_e32 v38, v31, v30
	ds_read_b128 v[30:33], v73 offset:36864
	ds_read_b128 v[34:37], v73 offset:37888
	v_mul_f32_e32 v39, v87, v45
	v_fmac_f32_e32 v39, v81, v41
	v_add_f32_e32 v29, v39, v29
	v_mul_f32_e32 v39, v119, v45
	v_fmac_f32_e32 v39, v117, v41
	v_add_f32_e32 v38, v39, v38
	s_waitcnt lgkmcnt(0)
	v_mul_f32_e32 v39, v96, v34
	v_mul_f32_e32 v34, v14, v34
	v_fmac_f32_e32 v34, v12, v30
	v_fmac_f32_e32 v39, v94, v30
	v_add_f32_e32 v30, v34, v38
	v_mul_f32_e32 v34, v97, v35
	v_add_f32_e32 v29, v39, v29
	v_fmac_f32_e32 v34, v95, v31
	v_add_f32_e32 v29, v34, v29
	v_mul_f32_e32 v34, v15, v35
	v_fmac_f32_e32 v34, v13, v31
	v_mul_f32_e32 v31, v92, v36
	v_fmac_f32_e32 v31, v90, v32
	v_add_f32_e32 v29, v31, v29
	v_mul_f32_e32 v31, v10, v36
	v_add_f32_e32 v30, v34, v30
	v_fmac_f32_e32 v31, v8, v32
	ds_read_b128 v[38:41], v73 offset:38912
	ds_read_b128 v[42:45], v73 offset:39936
	v_add_f32_e32 v30, v31, v30
	v_mul_f32_e32 v31, v93, v37
	v_fmac_f32_e32 v31, v91, v33
	v_add_f32_e32 v29, v31, v29
	v_mul_f32_e32 v31, v11, v37
	v_fmac_f32_e32 v31, v9, v33
	v_add_f32_e32 v30, v31, v30
	s_waitcnt lgkmcnt(0)
	v_mul_f32_e32 v31, v106, v42
	v_fmac_f32_e32 v31, v104, v38
	v_add_f32_e32 v29, v31, v29
	v_mul_f32_e32 v31, v20, v42
	v_fmac_f32_e32 v31, v18, v38
	v_add_f32_e32 v30, v31, v30
	v_mul_f32_e32 v31, v107, v43
	v_fmac_f32_e32 v31, v105, v39
	v_add_f32_e32 v29, v31, v29
	v_mul_f32_e32 v31, v21, v43
	v_fmac_f32_e32 v31, v19, v39
	v_add_f32_e32 v30, v31, v30
	v_mul_f32_e32 v31, v102, v44
	v_fmac_f32_e32 v31, v100, v40
	v_add_f32_e32 v29, v31, v29
	v_mul_f32_e32 v31, v6, v44
	v_fmac_f32_e32 v31, v16, v40
	ds_read_b128 v[32:35], v73 offset:40960
	ds_read_b128 v[36:39], v73 offset:41984
	v_add_f32_e32 v31, v31, v30
	v_mul_f32_e32 v30, v103, v45
	v_fmac_f32_e32 v30, v101, v41
	v_add_f32_e32 v30, v30, v29
	v_mul_f32_e32 v29, v7, v45
	v_fmac_f32_e32 v29, v17, v41
	v_add_f32_e32 v29, v29, v31
	s_waitcnt lgkmcnt(0)
	v_mul_f32_e32 v31, v82, v36
	v_mul_f32_e32 v36, v114, v36
	v_fmac_f32_e32 v36, v112, v32
	v_fmac_f32_e32 v31, v78, v32
	v_add_f32_e32 v32, 0, v36
	v_mul_f32_e32 v36, v83, v37
	v_add_f32_e32 v31, 0, v31
	v_fmac_f32_e32 v36, v79, v33
	v_add_f32_e32 v31, v36, v31
	v_mul_f32_e32 v36, v115, v37
	v_fmac_f32_e32 v36, v113, v33
	v_mul_f32_e32 v33, v76, v38
	v_fmac_f32_e32 v33, v74, v34
	v_add_f32_e32 v31, v33, v31
	v_mul_f32_e32 v33, v110, v38
	v_add_f32_e32 v32, v36, v32
	v_fmac_f32_e32 v33, v108, v34
	ds_read_b128 v[40:43], v73 offset:43008
	ds_read_b128 v[44:47], v73 offset:44032
	v_add_f32_e32 v32, v33, v32
	v_mul_f32_e32 v33, v77, v39
	v_fmac_f32_e32 v33, v75, v35
	v_add_f32_e32 v31, v33, v31
	v_mul_f32_e32 v33, v111, v39
	v_fmac_f32_e32 v33, v109, v35
	v_add_f32_e32 v32, v33, v32
	s_waitcnt lgkmcnt(0)
	v_mul_f32_e32 v33, v88, v44
	v_fmac_f32_e32 v33, v84, v40
	v_add_f32_e32 v31, v33, v31
	v_mul_f32_e32 v33, v122, v44
	v_fmac_f32_e32 v33, v120, v40
	v_add_f32_e32 v32, v33, v32
	v_mul_f32_e32 v33, v89, v45
	v_fmac_f32_e32 v33, v85, v41
	v_add_f32_e32 v31, v33, v31
	v_mul_f32_e32 v33, v123, v45
	v_fmac_f32_e32 v33, v121, v41
	v_add_f32_e32 v32, v33, v32
	v_mul_f32_e32 v33, v86, v46
	v_fmac_f32_e32 v33, v80, v42
	v_add_f32_e32 v31, v33, v31
	v_mul_f32_e32 v33, v118, v46
	v_fmac_f32_e32 v33, v116, v42
	v_add_f32_e32 v40, v33, v32
	ds_read_b128 v[32:35], v73 offset:45056
	ds_read_b128 v[36:39], v73 offset:46080
	v_mul_f32_e32 v41, v87, v47
	v_fmac_f32_e32 v41, v81, v43
	v_add_f32_e32 v31, v41, v31
	v_mul_f32_e32 v41, v119, v47
	v_fmac_f32_e32 v41, v117, v43
	v_add_f32_e32 v40, v41, v40
	s_waitcnt lgkmcnt(0)
; #define LAS __attribute__((address_space(3)))
; template <bool ZP, bool XF32, bool OUT8 = false>
; __device__ __forceinline__ void norm_phase(LAS unsigned char* lds, const void* xin, const float* gain, const float* sh, const float* sc, bf16* hout, const float* wzt, float* zout, int lane, int wave, int vcu, int G) {
;     ...
;         if constexpr (ZP) {
;             float p0[16], p1[16];
; #pragma unroll
;             for (int rr = 0; rr < 16; ++rr) { p0[rr] = 0.f; p1[rr] = 0.f;
; #pragma unroll
;                 for (int j = 0; j < 4; ++j) { const f32x4 w0 = *(const LAS f32x4*)(wl + (((rr * 4 + j) * 2 + 0) * 64 + lane) * 4), w1 = *(const LAS f32x4*)(wl + (((rr * 4 + j) * 2 + 1) * 64 + lane) * 4);
; #pragma unroll
;                     for (int e = 0; e < 4; ++e) { p0[rr] += v[0][j][0][e] * w0[e] + v[0][j][1][e] * w1[e]; p1[rr] += v[1][j][0][e] * w0[e] + v[1][j][1][e] * w1[e]; } } }
	v_mul_f32_e32 v41, v96, v36
	v_mul_f32_e32 v36, v14, v36
	v_fmac_f32_e32 v36, v12, v32
	v_fmac_f32_e32 v41, v94, v32
	v_add_f32_e32 v32, v36, v40
	v_mul_f32_e32 v36, v97, v37
	v_add_f32_e32 v31, v41, v31
	v_fmac_f32_e32 v36, v95, v33
	v_add_f32_e32 v31, v36, v31
	v_mul_f32_e32 v36, v15, v37
	v_fmac_f32_e32 v36, v13, v33
	v_mul_f32_e32 v33, v92, v38
	v_fmac_f32_e32 v33, v90, v34
	v_add_f32_e32 v31, v33, v31
	v_mul_f32_e32 v33, v10, v38
	v_add_f32_e32 v32, v36, v32
	v_fmac_f32_e32 v33, v8, v34
	ds_read_b128 v[40:43], v73 offset:47104
	ds_read_b128 v[44:47], v73 offset:48128
	v_add_f32_e32 v32, v33, v32
	v_mul_f32_e32 v33, v93, v39
	v_fmac_f32_e32 v33, v91, v35
	v_add_f32_e32 v31, v33, v31
	v_mul_f32_e32 v33, v11, v39
	v_fmac_f32_e32 v33, v9, v35
	v_add_f32_e32 v32, v33, v32
	s_waitcnt lgkmcnt(0)
	v_mul_f32_e32 v33, v106, v44
	v_fmac_f32_e32 v33, v104, v40
	v_add_f32_e32 v31, v33, v31
	v_mul_f32_e32 v33, v20, v44
	v_fmac_f32_e32 v33, v18, v40
	v_add_f32_e32 v32, v33, v32
	v_mul_f32_e32 v33, v107, v45
	v_fmac_f32_e32 v33, v105, v41
	v_add_f32_e32 v31, v33, v31
	v_mul_f32_e32 v33, v21, v45
	v_fmac_f32_e32 v33, v19, v41
	v_add_f32_e32 v32, v33, v32
	v_mul_f32_e32 v33, v102, v46
	v_fmac_f32_e32 v33, v100, v42
	v_add_f32_e32 v31, v33, v31
	v_mul_f32_e32 v33, v6, v46
	v_fmac_f32_e32 v33, v16, v42
	ds_read_b128 v[34:37], v73 offset:49152
	ds_read_b128 v[38:41], v73 offset:50176
	v_add_f32_e32 v33, v33, v32
	v_mul_f32_e32 v32, v103, v47
	v_fmac_f32_e32 v32, v101, v43
	v_add_f32_e32 v32, v32, v31
	v_mul_f32_e32 v31, v7, v47
	v_fmac_f32_e32 v31, v17, v43
	v_add_f32_e32 v31, v31, v33
	s_waitcnt lgkmcnt(0)
	v_mul_f32_e32 v33, v82, v38
	v_mul_f32_e32 v38, v114, v38
	v_fmac_f32_e32 v38, v112, v34
	v_fmac_f32_e32 v33, v78, v34
	v_add_f32_e32 v34, 0, v38
	v_mul_f32_e32 v38, v83, v39
	v_add_f32_e32 v33, 0, v33
	v_fmac_f32_e32 v38, v79, v35
	v_add_f32_e32 v33, v38, v33
	v_mul_f32_e32 v38, v115, v39
	v_fmac_f32_e32 v38, v113, v35
	v_mul_f32_e32 v35, v76, v40
	v_fmac_f32_e32 v35, v74, v36
	v_add_f32_e32 v33, v35, v33
	v_mul_f32_e32 v35, v110, v40
	v_add_f32_e32 v34, v38, v34
	v_fmac_f32_e32 v35, v108, v36
	ds_read_b128 v[42:45], v73 offset:51200
	ds_read_b128 v[46:49], v73 offset:52224
	v_add_f32_e32 v34, v35, v34
	v_mul_f32_e32 v35, v77, v41
	v_fmac_f32_e32 v35, v75, v37
	v_add_f32_e32 v33, v35, v33
	v_mul_f32_e32 v35, v111, v41
	v_fmac_f32_e32 v35, v109, v37
	v_add_f32_e32 v34, v35, v34
	s_waitcnt lgkmcnt(0)
	v_mul_f32_e32 v35, v88, v46
	v_fmac_f32_e32 v35, v84, v42
	v_add_f32_e32 v33, v35, v33
	v_mul_f32_e32 v35, v122, v46
	v_fmac_f32_e32 v35, v120, v42
	v_add_f32_e32 v34, v35, v34
	v_mul_f32_e32 v35, v89, v47
	v_fmac_f32_e32 v35, v85, v43
	v_add_f32_e32 v33, v35, v33
	v_mul_f32_e32 v35, v123, v47
	v_fmac_f32_e32 v35, v121, v43
	v_add_f32_e32 v34, v35, v34
	v_mul_f32_e32 v35, v86, v48
	v_fmac_f32_e32 v35, v80, v44
	v_add_f32_e32 v33, v35, v33
	v_mul_f32_e32 v35, v118, v48
	v_fmac_f32_e32 v35, v116, v44
	v_add_f32_e32 v42, v35, v34
	ds_read_b128 v[34:37], v73 offset:53248
	ds_read_b128 v[38:41], v73 offset:54272
	v_mul_f32_e32 v43, v87, v49
	v_fmac_f32_e32 v43, v81, v45
	v_add_f32_e32 v33, v43, v33
	v_mul_f32_e32 v43, v119, v49
	v_fmac_f32_e32 v43, v117, v45
	v_add_f32_e32 v42, v43, v42
	s_waitcnt lgkmcnt(0)
	v_mul_f32_e32 v43, v96, v38
	v_mul_f32_e32 v38, v14, v38
	v_fmac_f32_e32 v38, v12, v34
	v_fmac_f32_e32 v43, v94, v34
	v_add_f32_e32 v34, v38, v42
	v_mul_f32_e32 v38, v97, v39
	v_add_f32_e32 v33, v43, v33
	v_fmac_f32_e32 v38, v95, v35
	v_add_f32_e32 v33, v38, v33
	v_mul_f32_e32 v38, v15, v39
	v_fmac_f32_e32 v38, v13, v35
	v_mul_f32_e32 v35, v92, v40
	v_fmac_f32_e32 v35, v90, v36
	v_add_f32_e32 v33, v35, v33
	v_mul_f32_e32 v35, v10, v40
	v_add_f32_e32 v34, v38, v34
	v_fmac_f32_e32 v35, v8, v36
	ds_read_b128 v[42:45], v73 offset:55296
	ds_read_b128 v[46:49], v73 offset:56320
	v_add_f32_e32 v34, v35, v34
	v_mul_f32_e32 v35, v93, v41
	v_fmac_f32_e32 v35, v91, v37
	v_add_f32_e32 v33, v35, v33
	v_mul_f32_e32 v35, v11, v41
	v_fmac_f32_e32 v35, v9, v37
	v_add_f32_e32 v34, v35, v34
	s_waitcnt lgkmcnt(0)
	v_mul_f32_e32 v35, v106, v46
	v_fmac_f32_e32 v35, v104, v42
	v_add_f32_e32 v33, v35, v33
	v_mul_f32_e32 v35, v20, v46
	v_fmac_f32_e32 v35, v18, v42
	v_add_f32_e32 v34, v35, v34
	v_mul_f32_e32 v35, v107, v47
	v_fmac_f32_e32 v35, v105, v43
	v_add_f32_e32 v33, v35, v33
	v_mul_f32_e32 v35, v21, v47
	v_fmac_f32_e32 v35, v19, v43
	v_add_f32_e32 v34, v35, v34
	v_mul_f32_e32 v35, v102, v48
	v_fmac_f32_e32 v35, v100, v44
	v_add_f32_e32 v33, v35, v33
	v_mul_f32_e32 v35, v6, v48
	v_fmac_f32_e32 v35, v16, v44
	ds_read_b128 v[36:39], v73 offset:57344
	ds_read_b128 v[40:43], v73 offset:58368
	v_add_f32_e32 v35, v35, v34
	v_mul_f32_e32 v34, v103, v49
	v_fmac_f32_e32 v34, v101, v45
	v_add_f32_e32 v34, v34, v33
	v_mul_f32_e32 v33, v7, v49
	v_fmac_f32_e32 v33, v17, v45
	v_add_f32_e32 v33, v33, v35
	s_waitcnt lgkmcnt(0)
	v_mul_f32_e32 v35, v82, v40
	v_mul_f32_e32 v40, v114, v40
	v_fmac_f32_e32 v40, v112, v36
	v_fmac_f32_e32 v35, v78, v36
	v_add_f32_e32 v36, 0, v40
	v_mul_f32_e32 v40, v83, v41
	v_add_f32_e32 v35, 0, v35
	v_fmac_f32_e32 v40, v79, v37
	v_add_f32_e32 v35, v40, v35
	v_mul_f32_e32 v40, v115, v41
	v_fmac_f32_e32 v40, v113, v37
	v_mul_f32_e32 v37, v76, v42
	v_fmac_f32_e32 v37, v74, v38
	v_add_f32_e32 v35, v37, v35
	v_mul_f32_e32 v37, v110, v42
	v_add_f32_e32 v36, v40, v36
	v_fmac_f32_e32 v37, v108, v38
	ds_read_b128 v[44:47], v73 offset:59392
	ds_read_b128 v[48:51], v73 offset:60416
	v_add_f32_e32 v36, v37, v36
	v_mul_f32_e32 v37, v77, v43
	v_fmac_f32_e32 v37, v75, v39
	v_add_f32_e32 v35, v37, v35
	v_mul_f32_e32 v37, v111, v43
	v_fmac_f32_e32 v37, v109, v39
	v_add_f32_e32 v36, v37, v36
	s_waitcnt lgkmcnt(0)
; #define LAS __attribute__((address_space(3)))
; template <bool ZP, bool XF32, bool OUT8 = false>
; __device__ __forceinline__ void norm_phase(LAS unsigned char* lds, const void* xin, const float* gain, const float* sh, const float* sc, bf16* hout, const float* wzt, float* zout, int lane, int wave, int vcu, int G) {
;     ...
;         if constexpr (ZP) {
;             float p0[16], p1[16];
; #pragma unroll
;             for (int rr = 0; rr < 16; ++rr) { p0[rr] = 0.f; p1[rr] = 0.f;
; #pragma unroll
;                 for (int j = 0; j < 4; ++j) { const f32x4 w0 = *(const LAS f32x4*)(wl + (((rr * 4 + j) * 2 + 0) * 64 + lane) * 4), w1 = *(const LAS f32x4*)(wl + (((rr * 4 + j) * 2 + 1) * 64 + lane) * 4);
; #pragma unroll
;                     for (int e = 0; e < 4; ++e) { p0[rr] += v[0][j][0][e] * w0[e] + v[0][j][1][e] * w1[e]; p1[rr] += v[1][j][0][e] * w0[e] + v[1][j][1][e] * w1[e]; } } }
	v_mul_f32_e32 v37, v88, v48
	v_fmac_f32_e32 v37, v84, v44
	v_add_f32_e32 v35, v37, v35
	v_mul_f32_e32 v37, v122, v48
	v_fmac_f32_e32 v37, v120, v44
	v_add_f32_e32 v36, v37, v36
	v_mul_f32_e32 v37, v89, v49
	v_fmac_f32_e32 v37, v85, v45
	v_add_f32_e32 v35, v37, v35
	v_mul_f32_e32 v37, v123, v49
	v_fmac_f32_e32 v37, v121, v45
	v_add_f32_e32 v36, v37, v36
	v_mul_f32_e32 v37, v86, v50
	v_fmac_f32_e32 v37, v80, v46
	v_add_f32_e32 v35, v37, v35
	v_mul_f32_e32 v37, v118, v50
	v_fmac_f32_e32 v37, v116, v46
	v_add_f32_e32 v44, v37, v36
	ds_read_b128 v[36:39], v73 offset:61440
	ds_read_b128 v[40:43], v73 offset:62464
	v_mul_f32_e32 v45, v87, v51
	v_fmac_f32_e32 v45, v81, v47
	v_add_f32_e32 v35, v45, v35
	v_mul_f32_e32 v45, v119, v51
	v_fmac_f32_e32 v45, v117, v47
	v_add_f32_e32 v44, v45, v44
	s_waitcnt lgkmcnt(0)
	v_mul_f32_e32 v45, v96, v40
	v_mul_f32_e32 v40, v14, v40
	v_fmac_f32_e32 v40, v12, v36
	v_fmac_f32_e32 v45, v94, v36
	v_add_f32_e32 v36, v40, v44
	v_mul_f32_e32 v40, v97, v41
	v_add_f32_e32 v35, v45, v35
	v_fmac_f32_e32 v40, v95, v37
	v_add_f32_e32 v35, v40, v35
	v_mul_f32_e32 v40, v15, v41
	v_fmac_f32_e32 v40, v13, v37
	v_mul_f32_e32 v37, v92, v42
	v_fmac_f32_e32 v37, v90, v38
	v_add_f32_e32 v35, v37, v35
	v_mul_f32_e32 v37, v10, v42
	v_add_f32_e32 v36, v40, v36
	v_fmac_f32_e32 v37, v8, v38
	ds_read_b128 v[44:47], v73 offset:63488
	ds_read_b128 v[48:51], v73 offset:64512
	v_add_f32_e32 v36, v37, v36
	v_mul_f32_e32 v37, v93, v43
	v_fmac_f32_e32 v37, v91, v39
	v_add_f32_e32 v35, v37, v35
	v_mul_f32_e32 v37, v11, v43
	v_fmac_f32_e32 v37, v9, v39
	v_add_f32_e32 v36, v37, v36
	s_waitcnt lgkmcnt(0)
	v_mul_f32_e32 v37, v106, v48
	v_fmac_f32_e32 v37, v104, v44
	v_add_f32_e32 v35, v37, v35
	v_mul_f32_e32 v37, v20, v48
	v_fmac_f32_e32 v37, v18, v44
	v_add_f32_e32 v36, v37, v36
	v_mul_f32_e32 v37, v107, v49
	v_fmac_f32_e32 v37, v105, v45
	v_add_f32_e32 v35, v37, v35
	v_mul_f32_e32 v37, v21, v49
	v_fmac_f32_e32 v37, v19, v45
	v_add_f32_e32 v36, v37, v36
	v_mul_f32_e32 v37, v102, v50
	v_fmac_f32_e32 v37, v100, v46
	v_add_f32_e32 v35, v37, v35
	v_mul_f32_e32 v37, v6, v50
	v_fmac_f32_e32 v37, v16, v46
	ds_read_b128 v[38:41], v149
	ds_read_b128 v[42:45], v150
	v_add_f32_e32 v37, v37, v36
	v_mul_f32_e32 v36, v103, v51
	v_fmac_f32_e32 v36, v101, v47
	v_add_f32_e32 v36, v36, v35
	v_mul_f32_e32 v35, v7, v51
	v_fmac_f32_e32 v35, v17, v47
	v_add_f32_e32 v35, v35, v37
	s_waitcnt lgkmcnt(0)
	v_mul_f32_e32 v37, v82, v42
	v_mul_f32_e32 v42, v114, v42
	v_fmac_f32_e32 v42, v112, v38
	v_fmac_f32_e32 v37, v78, v38
	v_add_f32_e32 v38, 0, v42
	v_mul_f32_e32 v42, v83, v43
	v_add_f32_e32 v37, 0, v37
	v_fmac_f32_e32 v42, v79, v39
	v_add_f32_e32 v37, v42, v37
	v_mul_f32_e32 v42, v115, v43
	v_fmac_f32_e32 v42, v113, v39
	v_mul_f32_e32 v39, v76, v44
	v_fmac_f32_e32 v39, v74, v40
	v_add_f32_e32 v37, v39, v37
	v_mul_f32_e32 v39, v110, v44
	v_add_f32_e32 v38, v42, v38
	v_fmac_f32_e32 v39, v108, v40
	ds_read_b128 v[46:49], v151
	ds_read_b128 v[50:53], v152
	v_add_f32_e32 v38, v39, v38
	v_mul_f32_e32 v39, v77, v45
	v_fmac_f32_e32 v39, v75, v41
	v_add_f32_e32 v37, v39, v37
	v_mul_f32_e32 v39, v111, v45
	v_fmac_f32_e32 v39, v109, v41
	v_add_f32_e32 v38, v39, v38
	s_waitcnt lgkmcnt(0)
	v_mul_f32_e32 v39, v88, v50
	v_fmac_f32_e32 v39, v84, v46
	v_add_f32_e32 v37, v39, v37
	v_mul_f32_e32 v39, v122, v50
	v_fmac_f32_e32 v39, v120, v46
	v_add_f32_e32 v38, v39, v38
	v_mul_f32_e32 v39, v89, v51
	v_fmac_f32_e32 v39, v85, v47
	v_add_f32_e32 v37, v39, v37
	v_mul_f32_e32 v39, v123, v51
	v_fmac_f32_e32 v39, v121, v47
	v_add_f32_e32 v38, v39, v38
	v_mul_f32_e32 v39, v86, v52
	v_fmac_f32_e32 v39, v80, v48
	v_add_f32_e32 v37, v39, v37
	v_mul_f32_e32 v39, v118, v52
	v_fmac_f32_e32 v39, v116, v48
	v_add_f32_e32 v46, v39, v38
	ds_read_b128 v[38:41], v153
	ds_read_b128 v[42:45], v154
	v_mul_f32_e32 v47, v87, v53
	v_fmac_f32_e32 v47, v81, v49
	v_add_f32_e32 v37, v47, v37
	v_mul_f32_e32 v47, v119, v53
	v_fmac_f32_e32 v47, v117, v49
	v_add_f32_e32 v46, v47, v46
	s_waitcnt lgkmcnt(0)
	v_mul_f32_e32 v47, v96, v42
	v_mul_f32_e32 v42, v14, v42
	v_fmac_f32_e32 v42, v12, v38
	v_fmac_f32_e32 v47, v94, v38
	v_add_f32_e32 v38, v42, v46
	v_mul_f32_e32 v42, v97, v43
	v_add_f32_e32 v37, v47, v37
	v_fmac_f32_e32 v42, v95, v39
	v_add_f32_e32 v37, v42, v37
	v_mul_f32_e32 v42, v15, v43
	v_fmac_f32_e32 v42, v13, v39
	v_mul_f32_e32 v39, v92, v44
	v_fmac_f32_e32 v39, v90, v40
	v_add_f32_e32 v37, v39, v37
	v_mul_f32_e32 v39, v10, v44
	v_add_f32_e32 v38, v42, v38
	v_fmac_f32_e32 v39, v8, v40
	ds_read_b128 v[46:49], v155
	ds_read_b128 v[50:53], v156
	v_add_f32_e32 v38, v39, v38
	v_mul_f32_e32 v39, v93, v45
	v_fmac_f32_e32 v39, v91, v41
	v_add_f32_e32 v37, v39, v37
	v_mul_f32_e32 v39, v11, v45
	v_fmac_f32_e32 v39, v9, v41
	v_add_f32_e32 v38, v39, v38
	s_waitcnt lgkmcnt(0)
	v_mul_f32_e32 v39, v106, v50
	v_fmac_f32_e32 v39, v104, v46
	v_add_f32_e32 v37, v39, v37
	v_mul_f32_e32 v39, v20, v50
	v_fmac_f32_e32 v39, v18, v46
	v_add_f32_e32 v38, v39, v38
	v_mul_f32_e32 v39, v107, v51
	v_fmac_f32_e32 v39, v105, v47
	v_add_f32_e32 v37, v39, v37
	v_mul_f32_e32 v39, v21, v51
	v_fmac_f32_e32 v39, v19, v47
	v_add_f32_e32 v38, v39, v38
	v_mul_f32_e32 v39, v102, v52
	v_fmac_f32_e32 v39, v100, v48
	v_add_f32_e32 v37, v39, v37
	v_mul_f32_e32 v39, v6, v52
	v_fmac_f32_e32 v39, v16, v48
	ds_read_b128 v[40:43], v157
	ds_read_b128 v[44:47], v158
	v_add_f32_e32 v39, v39, v38
	v_mul_f32_e32 v38, v103, v53
	v_fmac_f32_e32 v38, v101, v49
	v_add_f32_e32 v38, v38, v37
	v_mul_f32_e32 v37, v7, v53
	v_fmac_f32_e32 v37, v17, v49
	v_add_f32_e32 v37, v37, v39
	s_waitcnt lgkmcnt(0)
; #define LAS __attribute__((address_space(3)))
; template <bool ZP, bool XF32, bool OUT8 = false>
; __device__ __forceinline__ void norm_phase(LAS unsigned char* lds, const void* xin, const float* gain, const float* sh, const float* sc, bf16* hout, const float* wzt, float* zout, int lane, int wave, int vcu, int G) {
;     ...
;         if constexpr (ZP) {
;             float p0[16], p1[16];
; #pragma unroll
;             for (int rr = 0; rr < 16; ++rr) { p0[rr] = 0.f; p1[rr] = 0.f;
; #pragma unroll
;                 for (int j = 0; j < 4; ++j) { const f32x4 w0 = *(const LAS f32x4*)(wl + (((rr * 4 + j) * 2 + 0) * 64 + lane) * 4), w1 = *(const LAS f32x4*)(wl + (((rr * 4 + j) * 2 + 1) * 64 + lane) * 4);
; #pragma unroll
;                     for (int e = 0; e < 4; ++e) { p0[rr] += v[0][j][0][e] * w0[e] + v[0][j][1][e] * w1[e]; p1[rr] += v[1][j][0][e] * w0[e] + v[1][j][1][e] * w1[e]; } } }
	v_mul_f32_e32 v39, v82, v44
	v_mul_f32_e32 v44, v114, v44
	v_fmac_f32_e32 v44, v112, v40
	v_fmac_f32_e32 v39, v78, v40
	v_add_f32_e32 v40, 0, v44
	v_mul_f32_e32 v44, v83, v45
	v_add_f32_e32 v39, 0, v39
	v_fmac_f32_e32 v44, v79, v41
	v_add_f32_e32 v39, v44, v39
	v_mul_f32_e32 v44, v115, v45
	v_fmac_f32_e32 v44, v113, v41
	v_mul_f32_e32 v41, v76, v46
	v_fmac_f32_e32 v41, v74, v42
	v_add_f32_e32 v39, v41, v39
	v_mul_f32_e32 v41, v110, v46
	v_add_f32_e32 v40, v44, v40
	v_fmac_f32_e32 v41, v108, v42
	ds_read_b128 v[48:51], v159
	ds_read_b128 v[52:55], v160
	v_add_f32_e32 v40, v41, v40
	v_mul_f32_e32 v41, v77, v47
	v_fmac_f32_e32 v41, v75, v43
	v_add_f32_e32 v39, v41, v39
	v_mul_f32_e32 v41, v111, v47
	v_fmac_f32_e32 v41, v109, v43
	v_add_f32_e32 v40, v41, v40
	s_waitcnt lgkmcnt(0)
	v_mul_f32_e32 v41, v88, v52
	v_fmac_f32_e32 v41, v84, v48
	v_add_f32_e32 v39, v41, v39
	v_mul_f32_e32 v41, v122, v52
	v_fmac_f32_e32 v41, v120, v48
	v_add_f32_e32 v40, v41, v40
	v_mul_f32_e32 v41, v89, v53
	v_fmac_f32_e32 v41, v85, v49
	v_add_f32_e32 v39, v41, v39
	v_mul_f32_e32 v41, v123, v53
	v_fmac_f32_e32 v41, v121, v49
	v_add_f32_e32 v40, v41, v40
	v_mul_f32_e32 v41, v86, v54
	v_fmac_f32_e32 v41, v80, v50
	v_add_f32_e32 v39, v41, v39
	v_mul_f32_e32 v41, v118, v54
	v_fmac_f32_e32 v41, v116, v50
	v_add_f32_e32 v48, v41, v40
	ds_read_b128 v[40:43], v161
	ds_read_b128 v[44:47], v162
	v_mul_f32_e32 v49, v87, v55
	v_fmac_f32_e32 v49, v81, v51
	v_add_f32_e32 v39, v49, v39
	v_mul_f32_e32 v49, v119, v55
	v_fmac_f32_e32 v49, v117, v51
	v_add_f32_e32 v48, v49, v48
	s_waitcnt lgkmcnt(0)
	v_mul_f32_e32 v49, v96, v44
	v_mul_f32_e32 v44, v14, v44
	v_fmac_f32_e32 v44, v12, v40
	v_fmac_f32_e32 v49, v94, v40
	v_add_f32_e32 v40, v44, v48
	v_mul_f32_e32 v44, v97, v45
	v_add_f32_e32 v39, v49, v39
	v_fmac_f32_e32 v44, v95, v41
	v_add_f32_e32 v39, v44, v39
	v_mul_f32_e32 v44, v15, v45
	v_fmac_f32_e32 v44, v13, v41
	v_mul_f32_e32 v41, v92, v46
	v_fmac_f32_e32 v41, v90, v42
	v_add_f32_e32 v39, v41, v39
	v_mul_f32_e32 v41, v10, v46
	v_add_f32_e32 v40, v44, v40
	v_fmac_f32_e32 v41, v8, v42
	ds_read_b128 v[48:51], v163
	ds_read_b128 v[52:55], v164
	v_add_f32_e32 v40, v41, v40
	v_mul_f32_e32 v41, v93, v47
	v_fmac_f32_e32 v41, v91, v43
	v_add_f32_e32 v39, v41, v39
	v_mul_f32_e32 v41, v11, v47
	v_fmac_f32_e32 v41, v9, v43
	v_add_f32_e32 v40, v41, v40
	s_waitcnt lgkmcnt(0)
	v_mul_f32_e32 v41, v106, v52
	v_fmac_f32_e32 v41, v104, v48
	v_add_f32_e32 v39, v41, v39
	v_mul_f32_e32 v41, v20, v52
	v_fmac_f32_e32 v41, v18, v48
	v_add_f32_e32 v40, v41, v40
	v_mul_f32_e32 v41, v107, v53
	v_fmac_f32_e32 v41, v105, v49
	v_add_f32_e32 v39, v41, v39
	v_mul_f32_e32 v41, v21, v53
	v_fmac_f32_e32 v41, v19, v49
	v_add_f32_e32 v40, v41, v40
	v_mul_f32_e32 v41, v102, v54
	v_fmac_f32_e32 v41, v100, v50
	v_add_f32_e32 v39, v41, v39
	v_mul_f32_e32 v41, v6, v54
	v_fmac_f32_e32 v41, v16, v50
	ds_read_b128 v[42:45], v165
	ds_read_b128 v[46:49], v166
	v_add_f32_e32 v41, v41, v40
	v_mul_f32_e32 v40, v103, v55
	v_fmac_f32_e32 v40, v101, v51
	v_add_f32_e32 v40, v40, v39
	v_mul_f32_e32 v39, v7, v55
	v_fmac_f32_e32 v39, v17, v51
	v_add_f32_e32 v39, v39, v41
	s_waitcnt lgkmcnt(0)
	v_mul_f32_e32 v41, v82, v46
	v_mul_f32_e32 v46, v114, v46
	v_fmac_f32_e32 v46, v112, v42
	v_fmac_f32_e32 v41, v78, v42
	v_add_f32_e32 v42, 0, v46
	v_mul_f32_e32 v46, v83, v47
	v_add_f32_e32 v41, 0, v41
	v_fmac_f32_e32 v46, v79, v43
	v_add_f32_e32 v41, v46, v41
	v_mul_f32_e32 v46, v115, v47
	v_fmac_f32_e32 v46, v113, v43
	v_mul_f32_e32 v43, v76, v48
	v_fmac_f32_e32 v43, v74, v44
	v_add_f32_e32 v41, v43, v41
	v_mul_f32_e32 v43, v110, v48
	v_add_f32_e32 v42, v46, v42
	v_fmac_f32_e32 v43, v108, v44
	ds_read_b128 v[50:53], v167
	ds_read_b128 v[54:57], v168
	v_add_f32_e32 v42, v43, v42
	v_mul_f32_e32 v43, v77, v49
	v_fmac_f32_e32 v43, v75, v45
	v_add_f32_e32 v41, v43, v41
	v_mul_f32_e32 v43, v111, v49
	v_fmac_f32_e32 v43, v109, v45
	v_add_f32_e32 v42, v43, v42
	s_waitcnt lgkmcnt(0)
	v_mul_f32_e32 v43, v88, v54
	v_fmac_f32_e32 v43, v84, v50
	v_add_f32_e32 v41, v43, v41
	v_mul_f32_e32 v43, v122, v54
	v_fmac_f32_e32 v43, v120, v50
	v_add_f32_e32 v42, v43, v42
	v_mul_f32_e32 v43, v89, v55
	v_fmac_f32_e32 v43, v85, v51
	v_add_f32_e32 v41, v43, v41
	v_mul_f32_e32 v43, v123, v55
	v_fmac_f32_e32 v43, v121, v51
	v_add_f32_e32 v42, v43, v42
	v_mul_f32_e32 v43, v86, v56
	v_fmac_f32_e32 v43, v80, v52
	v_add_f32_e32 v41, v43, v41
	v_mul_f32_e32 v43, v118, v56
	v_fmac_f32_e32 v43, v116, v52
	v_add_f32_e32 v50, v43, v42
	ds_read_b128 v[42:45], v169
	ds_read_b128 v[46:49], v170
	v_mul_f32_e32 v51, v87, v57
	v_fmac_f32_e32 v51, v81, v53
	v_add_f32_e32 v41, v51, v41
	v_mul_f32_e32 v51, v119, v57
	v_fmac_f32_e32 v51, v117, v53
	v_add_f32_e32 v50, v51, v50
	s_waitcnt lgkmcnt(0)
	v_mul_f32_e32 v51, v96, v46
	v_mul_f32_e32 v46, v14, v46
	v_fmac_f32_e32 v46, v12, v42
	v_fmac_f32_e32 v51, v94, v42
	v_add_f32_e32 v42, v46, v50
	v_mul_f32_e32 v46, v97, v47
	v_add_f32_e32 v41, v51, v41
	v_fmac_f32_e32 v46, v95, v43
	v_add_f32_e32 v41, v46, v41
	v_mul_f32_e32 v46, v15, v47
	v_fmac_f32_e32 v46, v13, v43
	v_mul_f32_e32 v43, v92, v48
	v_fmac_f32_e32 v43, v90, v44
	v_add_f32_e32 v41, v43, v41
	v_mul_f32_e32 v43, v10, v48
	v_add_f32_e32 v42, v46, v42
	v_fmac_f32_e32 v43, v8, v44
	ds_read_b128 v[50:53], v171
	ds_read_b128 v[54:57], v172
	v_add_f32_e32 v42, v43, v42
	v_mul_f32_e32 v43, v93, v49
	v_fmac_f32_e32 v43, v91, v45
	v_add_f32_e32 v41, v43, v41
	v_mul_f32_e32 v43, v11, v49
	v_fmac_f32_e32 v43, v9, v45
	v_add_f32_e32 v42, v43, v42
	s_waitcnt lgkmcnt(0)
; #define LAS __attribute__((address_space(3)))
; template <bool ZP, bool XF32, bool OUT8 = false>
; __device__ __forceinline__ void norm_phase(LAS unsigned char* lds, const void* xin, const float* gain, const float* sh, const float* sc, bf16* hout, const float* wzt, float* zout, int lane, int wave, int vcu, int G) {
;     ...
;         if constexpr (ZP) {
;             float p0[16], p1[16];
; #pragma unroll
;             for (int rr = 0; rr < 16; ++rr) { p0[rr] = 0.f; p1[rr] = 0.f;
; #pragma unroll
;                 for (int j = 0; j < 4; ++j) { const f32x4 w0 = *(const LAS f32x4*)(wl + (((rr * 4 + j) * 2 + 0) * 64 + lane) * 4), w1 = *(const LAS f32x4*)(wl + (((rr * 4 + j) * 2 + 1) * 64 + lane) * 4);
; #pragma unroll
;                     for (int e = 0; e < 4; ++e) { p0[rr] += v[0][j][0][e] * w0[e] + v[0][j][1][e] * w1[e]; p1[rr] += v[1][j][0][e] * w0[e] + v[1][j][1][e] * w1[e]; } } }
	v_mul_f32_e32 v43, v106, v54
	v_fmac_f32_e32 v43, v104, v50
	v_add_f32_e32 v41, v43, v41
	v_mul_f32_e32 v43, v20, v54
	v_fmac_f32_e32 v43, v18, v50
	v_add_f32_e32 v42, v43, v42
	v_mul_f32_e32 v43, v107, v55
	v_fmac_f32_e32 v43, v105, v51
	v_add_f32_e32 v41, v43, v41
	v_mul_f32_e32 v43, v21, v55
	v_fmac_f32_e32 v43, v19, v51
	v_add_f32_e32 v42, v43, v42
	v_mul_f32_e32 v43, v102, v56
	v_fmac_f32_e32 v43, v100, v52
	v_add_f32_e32 v41, v43, v41
	v_mul_f32_e32 v43, v6, v56
	v_fmac_f32_e32 v43, v16, v52
	ds_read_b128 v[44:47], v173
	ds_read_b128 v[48:51], v174
	v_add_f32_e32 v43, v43, v42
	v_mul_f32_e32 v42, v103, v57
	v_fmac_f32_e32 v42, v101, v53
	v_add_f32_e32 v42, v42, v41
	v_mul_f32_e32 v41, v7, v57
	v_fmac_f32_e32 v41, v17, v53
	v_add_f32_e32 v41, v41, v43
	s_waitcnt lgkmcnt(0)
	v_mul_f32_e32 v43, v82, v48
	v_mul_f32_e32 v48, v114, v48
	v_fmac_f32_e32 v48, v112, v44
	v_fmac_f32_e32 v43, v78, v44
	v_add_f32_e32 v44, 0, v48
	v_mul_f32_e32 v48, v83, v49
	v_add_f32_e32 v43, 0, v43
	v_fmac_f32_e32 v48, v79, v45
	v_add_f32_e32 v43, v48, v43
	v_mul_f32_e32 v48, v115, v49
	v_fmac_f32_e32 v48, v113, v45
	v_mul_f32_e32 v45, v76, v50
	v_fmac_f32_e32 v45, v74, v46
	v_add_f32_e32 v43, v45, v43
	v_mul_f32_e32 v45, v110, v50
	v_add_f32_e32 v44, v48, v44
	v_fmac_f32_e32 v45, v108, v46
	ds_read_b128 v[52:55], v175
	ds_read_b128 v[124:127], v176
	v_add_f32_e32 v44, v45, v44
	v_mul_f32_e32 v45, v77, v51
	v_fmac_f32_e32 v45, v75, v47
	v_add_f32_e32 v43, v45, v43
	v_mul_f32_e32 v45, v111, v51
	v_fmac_f32_e32 v45, v109, v47
	v_add_f32_e32 v44, v45, v44
	s_waitcnt lgkmcnt(0)
	v_mul_f32_e32 v45, v88, v124
	v_fmac_f32_e32 v45, v84, v52
	v_add_f32_e32 v43, v45, v43
	v_mul_f32_e32 v45, v122, v124
	v_fmac_f32_e32 v45, v120, v52
	v_add_f32_e32 v44, v45, v44
	v_mul_f32_e32 v45, v89, v125
	v_fmac_f32_e32 v45, v85, v53
	v_add_f32_e32 v43, v45, v43
	v_mul_f32_e32 v45, v123, v125
	v_fmac_f32_e32 v45, v121, v53
	v_add_f32_e32 v44, v45, v44
	v_mul_f32_e32 v45, v86, v126
	v_fmac_f32_e32 v45, v80, v54
	v_add_f32_e32 v43, v45, v43
	v_mul_f32_e32 v45, v118, v126
	v_fmac_f32_e32 v45, v116, v54
	v_add_f32_e32 v52, v45, v44
	ds_read_b128 v[44:47], v177
	ds_read_b128 v[48:51], v178
	v_mul_f32_e32 v53, v87, v127
	v_fmac_f32_e32 v53, v81, v55
	v_add_f32_e32 v43, v53, v43
	v_mul_f32_e32 v53, v119, v127
	v_fmac_f32_e32 v53, v117, v55
	v_add_f32_e32 v52, v53, v52
	s_waitcnt lgkmcnt(0)
	v_mul_f32_e32 v53, v96, v48
	v_mul_f32_e32 v48, v14, v48
	v_fmac_f32_e32 v48, v12, v44
	v_fmac_f32_e32 v53, v94, v44
	v_add_f32_e32 v44, v48, v52
	v_mul_f32_e32 v48, v97, v49
	v_add_f32_e32 v43, v53, v43
	v_fmac_f32_e32 v48, v95, v45
	v_add_f32_e32 v43, v48, v43
	v_mul_f32_e32 v48, v15, v49
	v_fmac_f32_e32 v48, v13, v45
	v_mul_f32_e32 v45, v92, v50
	v_fmac_f32_e32 v45, v90, v46
	v_add_f32_e32 v43, v45, v43
	v_mul_f32_e32 v45, v10, v50
	v_add_f32_e32 v44, v48, v44
	v_fmac_f32_e32 v45, v8, v46
	ds_read_b128 v[52:55], v179
	ds_read_b128 v[124:127], v180
	v_add_f32_e32 v44, v45, v44
	v_mul_f32_e32 v45, v93, v51
	v_fmac_f32_e32 v45, v91, v47
	v_add_f32_e32 v43, v45, v43
	v_mul_f32_e32 v45, v11, v51
	v_fmac_f32_e32 v45, v9, v47
	v_add_f32_e32 v44, v45, v44
	s_waitcnt lgkmcnt(0)
	v_mul_f32_e32 v45, v106, v124
	v_fmac_f32_e32 v45, v104, v52
	v_add_f32_e32 v43, v45, v43
	v_mul_f32_e32 v45, v20, v124
	v_fmac_f32_e32 v45, v18, v52
	v_add_f32_e32 v44, v45, v44
	v_mul_f32_e32 v45, v107, v125
	v_fmac_f32_e32 v45, v105, v53
	v_add_f32_e32 v43, v45, v43
	v_mul_f32_e32 v45, v21, v125
	v_fmac_f32_e32 v45, v19, v53
	v_add_f32_e32 v44, v45, v44
	v_mul_f32_e32 v45, v102, v126
	v_fmac_f32_e32 v45, v100, v54
	v_add_f32_e32 v43, v45, v43
	v_mul_f32_e32 v45, v6, v126
	v_fmac_f32_e32 v45, v16, v54
	ds_read_b128 v[46:49], v181
	ds_read_b128 v[50:53], v182
	v_add_f32_e32 v45, v45, v44
	v_mul_f32_e32 v44, v103, v127
	v_fmac_f32_e32 v44, v101, v55
	v_add_f32_e32 v44, v44, v43
	v_mul_f32_e32 v43, v7, v127
	v_fmac_f32_e32 v43, v17, v55
	v_add_f32_e32 v43, v43, v45
	s_waitcnt lgkmcnt(0)
	v_mul_f32_e32 v45, v82, v50
	v_mul_f32_e32 v50, v114, v50
	v_fmac_f32_e32 v50, v112, v46
	v_fmac_f32_e32 v45, v78, v46
	v_add_f32_e32 v46, 0, v50
	v_mul_f32_e32 v50, v83, v51
	v_add_f32_e32 v45, 0, v45
	v_fmac_f32_e32 v50, v79, v47
	v_add_f32_e32 v45, v50, v45
	v_mul_f32_e32 v50, v115, v51
	v_fmac_f32_e32 v50, v113, v47
	v_mul_f32_e32 v47, v76, v52
	v_fmac_f32_e32 v47, v74, v48
	v_add_f32_e32 v45, v47, v45
	v_mul_f32_e32 v47, v110, v52
	v_add_f32_e32 v46, v50, v46
	v_fmac_f32_e32 v47, v108, v48
	ds_read_b128 v[54:57], v183
	ds_read_b128 v[124:127], v184
	v_add_f32_e32 v46, v47, v46
	v_mul_f32_e32 v47, v77, v53
	v_fmac_f32_e32 v47, v75, v49
	v_add_f32_e32 v45, v47, v45
	v_mul_f32_e32 v47, v111, v53
	v_fmac_f32_e32 v47, v109, v49
	v_add_f32_e32 v46, v47, v46
	s_waitcnt lgkmcnt(0)
	v_mul_f32_e32 v47, v88, v124
	v_fmac_f32_e32 v47, v84, v54
	v_add_f32_e32 v45, v47, v45
	v_mul_f32_e32 v47, v122, v124
	v_fmac_f32_e32 v47, v120, v54
	v_add_f32_e32 v46, v47, v46
	v_mul_f32_e32 v47, v89, v125
	v_fmac_f32_e32 v47, v85, v55
	v_add_f32_e32 v45, v47, v45
	v_mul_f32_e32 v47, v123, v125
	v_fmac_f32_e32 v47, v121, v55
	v_add_f32_e32 v46, v47, v46
	v_mul_f32_e32 v47, v86, v126
	v_fmac_f32_e32 v47, v80, v56
	v_add_f32_e32 v45, v47, v45
	v_mul_f32_e32 v47, v118, v126
	v_fmac_f32_e32 v47, v116, v56
	v_add_f32_e32 v54, v47, v46
	ds_read_b128 v[46:49], v185
	ds_read_b128 v[50:53], v186
	v_mul_f32_e32 v55, v87, v127
	v_fmac_f32_e32 v55, v81, v57
	v_add_f32_e32 v45, v55, v45
	v_mul_f32_e32 v55, v119, v127
	v_fmac_f32_e32 v55, v117, v57
	v_add_f32_e32 v54, v55, v54
	s_waitcnt lgkmcnt(0)
; #define LAS __attribute__((address_space(3)))
; template <bool ZP, bool XF32, bool OUT8 = false>
; __device__ __forceinline__ void norm_phase(LAS unsigned char* lds, const void* xin, const float* gain, const float* sh, const float* sc, bf16* hout, const float* wzt, float* zout, int lane, int wave, int vcu, int G) {
;     ...
;         if constexpr (ZP) {
;             float p0[16], p1[16];
; #pragma unroll
;             for (int rr = 0; rr < 16; ++rr) { p0[rr] = 0.f; p1[rr] = 0.f;
; #pragma unroll
;                 for (int j = 0; j < 4; ++j) { const f32x4 w0 = *(const LAS f32x4*)(wl + (((rr * 4 + j) * 2 + 0) * 64 + lane) * 4), w1 = *(const LAS f32x4*)(wl + (((rr * 4 + j) * 2 + 1) * 64 + lane) * 4);
; #pragma unroll
;                     for (int e = 0; e < 4; ++e) { p0[rr] += v[0][j][0][e] * w0[e] + v[0][j][1][e] * w1[e]; p1[rr] += v[1][j][0][e] * w0[e] + v[1][j][1][e] * w1[e]; } } }
	v_mul_f32_e32 v55, v96, v50
	v_mul_f32_e32 v50, v14, v50
	v_fmac_f32_e32 v50, v12, v46
	v_fmac_f32_e32 v55, v94, v46
	v_add_f32_e32 v46, v50, v54
	v_mul_f32_e32 v50, v97, v51
	v_add_f32_e32 v45, v55, v45
	v_fmac_f32_e32 v50, v95, v47
	v_add_f32_e32 v45, v50, v45
	v_mul_f32_e32 v50, v15, v51
	v_fmac_f32_e32 v50, v13, v47
	v_mul_f32_e32 v47, v92, v52
	v_fmac_f32_e32 v47, v90, v48
	v_add_f32_e32 v45, v47, v45
	v_mul_f32_e32 v47, v10, v52
	v_add_f32_e32 v46, v50, v46
	v_fmac_f32_e32 v47, v8, v48
	ds_read_b128 v[54:57], v187
	ds_read_b128 v[124:127], v188
	v_add_f32_e32 v46, v47, v46
	v_mul_f32_e32 v47, v93, v53
	v_fmac_f32_e32 v47, v91, v49
	v_add_f32_e32 v45, v47, v45
	v_mul_f32_e32 v47, v11, v53
	v_fmac_f32_e32 v47, v9, v49
	v_add_f32_e32 v46, v47, v46
	s_waitcnt lgkmcnt(0)
	v_mul_f32_e32 v47, v106, v124
	v_fmac_f32_e32 v47, v104, v54
	v_add_f32_e32 v45, v47, v45
	v_mul_f32_e32 v47, v20, v124
	v_fmac_f32_e32 v47, v18, v54
	v_add_f32_e32 v46, v47, v46
	v_mul_f32_e32 v47, v107, v125
	v_fmac_f32_e32 v47, v105, v55
	v_add_f32_e32 v45, v47, v45
	v_mul_f32_e32 v47, v21, v125
	v_fmac_f32_e32 v47, v19, v55
	v_add_f32_e32 v46, v47, v46
	v_mul_f32_e32 v47, v102, v126
	v_fmac_f32_e32 v47, v100, v56
	v_add_f32_e32 v45, v47, v45
	v_mul_f32_e32 v47, v6, v126
	v_fmac_f32_e32 v47, v16, v56
	v_add_f32_e32 v54, v47, v46
	ds_read_b128 v[46:49], v189
	ds_read_b128 v[50:53], v190
	v_mul_f32_e32 v55, v103, v127
	v_fmac_f32_e32 v55, v101, v57
	v_add_f32_e32 v128, v55, v45
	v_mul_f32_e32 v45, v7, v127
	v_fmac_f32_e32 v45, v17, v57
	v_add_f32_e32 v45, v45, v54
	s_waitcnt lgkmcnt(0)
	v_mul_f32_e32 v54, v82, v50
	v_mul_f32_e32 v50, v114, v50
	v_fmac_f32_e32 v50, v112, v46
	v_fmac_f32_e32 v54, v78, v46
	v_add_f32_e32 v46, 0, v50
	v_mul_f32_e32 v50, v83, v51
	v_mul_f32_e32 v51, v115, v51
	v_add_f32_e32 v54, 0, v54
	v_fmac_f32_e32 v50, v79, v47
	v_fmac_f32_e32 v51, v113, v47
	v_mul_f32_e32 v47, v76, v52
	v_add_f32_e32 v50, v50, v54
	v_fmac_f32_e32 v47, v74, v48
	v_add_f32_e32 v47, v47, v50
	v_mul_f32_e32 v50, v110, v52
	ds_read_b128 v[54:57], v191
	ds_read_b128 v[124:127], v192
	v_fmac_f32_e32 v50, v108, v48
	v_mul_f32_e32 v48, v77, v53
	v_fmac_f32_e32 v48, v75, v49
	v_add_f32_e32 v46, v51, v46
	v_add_f32_e32 v47, v48, v47
	v_mul_f32_e32 v48, v111, v53
	v_add_f32_e32 v46, v50, v46
	v_fmac_f32_e32 v48, v109, v49
	v_add_f32_e32 v46, v48, v46
	s_waitcnt lgkmcnt(0)
	v_mul_f32_e32 v48, v88, v124
	v_fmac_f32_e32 v48, v84, v54
	v_add_f32_e32 v47, v48, v47
	v_mul_f32_e32 v48, v122, v124
	v_fmac_f32_e32 v48, v120, v54
	v_add_f32_e32 v46, v48, v46
	v_mul_f32_e32 v48, v89, v125
	v_fmac_f32_e32 v48, v85, v55
	v_add_f32_e32 v47, v48, v47
	v_mul_f32_e32 v48, v123, v125
	v_fmac_f32_e32 v48, v121, v55
	v_add_f32_e32 v46, v48, v46
	v_mul_f32_e32 v48, v86, v126
	v_fmac_f32_e32 v48, v80, v56
	v_add_f32_e32 v54, v48, v47
	v_mul_f32_e32 v47, v118, v126
	v_fmac_f32_e32 v47, v116, v56
	v_add_f32_e32 v55, v47, v46
	ds_read_b128 v[46:49], v193
	ds_read_b128 v[50:53], v194
	v_mul_f32_e32 v56, v87, v127
	v_fmac_f32_e32 v56, v81, v57
	v_add_f32_e32 v54, v56, v54
	v_mul_f32_e32 v56, v119, v127
	v_fmac_f32_e32 v56, v117, v57
	v_add_f32_e32 v55, v56, v55
	s_waitcnt lgkmcnt(0)
	v_mul_f32_e32 v56, v96, v50
	v_mul_f32_e32 v50, v14, v50
	v_fmac_f32_e32 v50, v12, v46
	v_fmac_f32_e32 v56, v94, v46
	v_add_f32_e32 v46, v50, v55
	v_mul_f32_e32 v50, v97, v51
	v_mul_f32_e32 v51, v15, v51
	v_add_f32_e32 v54, v56, v54
	v_fmac_f32_e32 v50, v95, v47
	v_fmac_f32_e32 v51, v13, v47
	v_mul_f32_e32 v47, v92, v52
	v_add_f32_e32 v50, v50, v54
	v_fmac_f32_e32 v47, v90, v48
	v_add_f32_e32 v47, v47, v50
	v_mul_f32_e32 v50, v10, v52
	ds_read_b128 v[54:57], v195
	ds_read_b128 v[124:127], v196
	v_fmac_f32_e32 v50, v8, v48
	v_mul_f32_e32 v48, v93, v53
	v_fmac_f32_e32 v48, v91, v49
	v_add_f32_e32 v46, v51, v46
	v_add_f32_e32 v47, v48, v47
	v_mul_f32_e32 v48, v11, v53
	v_add_f32_e32 v46, v50, v46
	v_fmac_f32_e32 v48, v9, v49
	v_add_f32_e32 v46, v48, v46
	s_waitcnt lgkmcnt(0)
	v_mul_f32_e32 v48, v106, v124
	v_fmac_f32_e32 v48, v104, v54
	v_add_f32_e32 v47, v48, v47
	v_mul_f32_e32 v48, v20, v124
	v_fmac_f32_e32 v48, v18, v54
	v_add_f32_e32 v46, v48, v46
	v_mul_f32_e32 v48, v107, v125
	v_fmac_f32_e32 v48, v105, v55
	v_add_f32_e32 v47, v48, v47
	v_mul_f32_e32 v48, v21, v125
	v_fmac_f32_e32 v48, v19, v55
	v_add_f32_e32 v46, v48, v46
	v_mul_f32_e32 v48, v102, v126
	v_fmac_f32_e32 v48, v100, v56
	v_add_f32_e32 v54, v48, v47
	v_mul_f32_e32 v47, v6, v126
	v_fmac_f32_e32 v47, v16, v56
	v_add_f32_e32 v55, v47, v46
	ds_read_b128 v[46:49], v197
	ds_read_b128 v[50:53], v198
	v_mul_f32_e32 v56, v103, v127
	v_fmac_f32_e32 v56, v101, v57
	v_add_f32_e32 v129, v56, v54
	v_mul_f32_e32 v54, v7, v127
	v_fmac_f32_e32 v54, v17, v57
	v_add_f32_e32 v130, v54, v55
	s_waitcnt lgkmcnt(0)
	v_mul_f32_e32 v54, v82, v50
	v_mul_f32_e32 v50, v114, v50
	v_fmac_f32_e32 v50, v112, v46
	v_fmac_f32_e32 v54, v78, v46
	v_add_f32_e32 v46, 0, v50
	v_mul_f32_e32 v50, v83, v51
	v_mul_f32_e32 v51, v115, v51
	v_add_f32_e32 v54, 0, v54
	v_fmac_f32_e32 v50, v79, v47
	v_fmac_f32_e32 v51, v113, v47
	v_mul_f32_e32 v47, v76, v52
	v_add_f32_e32 v50, v50, v54
	v_fmac_f32_e32 v47, v74, v48
	v_add_f32_e32 v47, v47, v50
	v_mul_f32_e32 v50, v110, v52
	ds_read_b128 v[54:57], v199
	ds_read_b128 v[124:127], v200
	v_fmac_f32_e32 v50, v108, v48
	v_mul_f32_e32 v48, v77, v53
	v_fmac_f32_e32 v48, v75, v49
	v_add_f32_e32 v46, v51, v46
	v_add_f32_e32 v47, v48, v47
	v_mul_f32_e32 v48, v111, v53
	v_add_f32_e32 v46, v50, v46
	v_fmac_f32_e32 v48, v109, v49
	v_add_f32_e32 v46, v48, v46
	s_waitcnt lgkmcnt(0)
; #define LAS __attribute__((address_space(3)))
; __device__ __forceinline__ float reduce16(const float (&p)[16], int lane) {
;     float a[8], b[4], c[2];
;     { const bool hi = (lane & 32) != 0;
; #pragma unroll
;       for (int k = 0; k < 8; ++k) { const float send = hi ? p[k] : p[k + 8], keep = hi ? p[k + 8] : p[k]; a[k] = keep + __shfl_xor(send, 32); } }
; template <bool ZP, bool XF32, bool OUT8 = false>
; __device__ __forceinline__ void norm_phase(LAS unsigned char* lds, const void* xin, const float* gain, const float* sh, const float* sc, bf16* hout, const float* wzt, float* zout, int lane, int wave, int vcu, int G) {
;     ...
;         if constexpr (ZP) {
;             float p0[16], p1[16];
; #pragma unroll
;             for (int rr = 0; rr < 16; ++rr) { p0[rr] = 0.f; p1[rr] = 0.f;
; #pragma unroll
;                 for (int j = 0; j < 4; ++j) { const f32x4 w0 = *(const LAS f32x4*)(wl + (((rr * 4 + j) * 2 + 0) * 64 + lane) * 4), w1 = *(const LAS f32x4*)(wl + (((rr * 4 + j) * 2 + 1) * 64 + lane) * 4);
; #pragma unroll
;                     for (int e = 0; e < 4; ++e) { p0[rr] += v[0][j][0][e] * w0[e] + v[0][j][1][e] * w1[e]; p1[rr] += v[1][j][0][e] * w0[e] + v[1][j][1][e] * w1[e]; } } }
;             const float z0 = reduce16(p0, lane), z1 = reduce16(p1, lane);
	v_mul_f32_e32 v48, v88, v124
	v_fmac_f32_e32 v48, v84, v54
	v_add_f32_e32 v47, v48, v47
	v_mul_f32_e32 v48, v122, v124
	v_fmac_f32_e32 v48, v120, v54
	v_add_f32_e32 v46, v48, v46
	v_mul_f32_e32 v48, v89, v125
	v_fmac_f32_e32 v48, v85, v55
	v_add_f32_e32 v47, v48, v47
	v_mul_f32_e32 v48, v123, v125
	v_fmac_f32_e32 v48, v121, v55
	v_add_f32_e32 v46, v48, v46
	v_mul_f32_e32 v48, v86, v126
	v_fmac_f32_e32 v48, v80, v56
	v_add_f32_e32 v54, v48, v47
	v_mul_f32_e32 v47, v118, v126
	v_fmac_f32_e32 v47, v116, v56
	v_add_f32_e32 v55, v47, v46
	ds_read_b128 v[46:49], v201
	ds_read_b128 v[50:53], v202
	v_mul_f32_e32 v56, v87, v127
	v_fmac_f32_e32 v56, v81, v57
	v_add_f32_e32 v54, v56, v54
	v_mul_f32_e32 v56, v119, v127
	v_fmac_f32_e32 v56, v117, v57
	v_add_f32_e32 v55, v56, v55
	s_waitcnt lgkmcnt(0)
	v_mul_f32_e32 v56, v96, v50
	v_mul_f32_e32 v50, v14, v50
	v_fmac_f32_e32 v50, v12, v46
	v_fmac_f32_e32 v56, v94, v46
	v_add_f32_e32 v46, v50, v55
	v_mul_f32_e32 v50, v97, v51
	v_mul_f32_e32 v51, v15, v51
	v_add_f32_e32 v54, v56, v54
	v_fmac_f32_e32 v50, v95, v47
	v_fmac_f32_e32 v51, v13, v47
	v_mul_f32_e32 v47, v92, v52
	v_add_f32_e32 v50, v50, v54
	v_fmac_f32_e32 v47, v90, v48
	v_add_f32_e32 v47, v47, v50
	v_mul_f32_e32 v50, v10, v52
	ds_read_b128 v[54:57], v203
	ds_read_b128 v[124:127], v204
	v_fmac_f32_e32 v50, v8, v48
	v_mul_f32_e32 v48, v93, v53
	v_fmac_f32_e32 v48, v91, v49
	v_add_f32_e32 v46, v51, v46
	v_add_f32_e32 v47, v48, v47
	v_mul_f32_e32 v48, v11, v53
	v_add_f32_e32 v46, v50, v46
	v_fmac_f32_e32 v48, v9, v49
	v_add_f32_e32 v46, v48, v46
	s_waitcnt lgkmcnt(0)
	v_mul_f32_e32 v48, v106, v124
	v_fmac_f32_e32 v48, v104, v54
	v_add_f32_e32 v47, v48, v47
	v_mul_f32_e32 v48, v20, v124
	v_fmac_f32_e32 v48, v18, v54
	v_add_f32_e32 v46, v48, v46
	v_mul_f32_e32 v48, v107, v125
	v_fmac_f32_e32 v48, v105, v55
	v_add_f32_e32 v47, v48, v47
	v_mul_f32_e32 v48, v21, v125
	v_fmac_f32_e32 v48, v19, v55
	v_add_f32_e32 v46, v48, v46
	v_mul_f32_e32 v48, v102, v126
	v_fmac_f32_e32 v48, v100, v56
	v_add_f32_e32 v54, v48, v47
	v_mul_f32_e32 v47, v6, v126
	v_fmac_f32_e32 v47, v16, v56
	v_add_f32_e32 v55, v47, v46
	ds_read_b128 v[46:49], v205
	ds_read_b128 v[50:53], v206
	v_mul_f32_e32 v56, v103, v127
	v_fmac_f32_e32 v56, v101, v57
	v_add_f32_e32 v124, v56, v54
	v_mul_f32_e32 v54, v7, v127
	v_fmac_f32_e32 v54, v17, v57
	v_add_f32_e32 v125, v54, v55
	s_waitcnt lgkmcnt(0)
	v_mul_f32_e32 v54, v82, v50
	v_mul_f32_e32 v50, v114, v50
	v_fmac_f32_e32 v50, v112, v46
	v_fmac_f32_e32 v54, v78, v46
	v_add_f32_e32 v46, 0, v50
	v_mul_f32_e32 v50, v83, v51
	v_mul_f32_e32 v51, v115, v51
	v_add_f32_e32 v54, 0, v54
	v_fmac_f32_e32 v50, v79, v47
	v_fmac_f32_e32 v51, v113, v47
	v_mul_f32_e32 v47, v76, v52
	v_add_f32_e32 v50, v50, v54
	v_fmac_f32_e32 v47, v74, v48
	v_add_f32_e32 v47, v47, v50
	v_mul_f32_e32 v50, v110, v52
	v_fmac_f32_e32 v50, v108, v48
	v_mul_f32_e32 v48, v77, v53
	v_fmac_f32_e32 v48, v75, v49
	ds_read_b128 v[54:57], v207
	ds_read_b128 v[74:77], v208
	v_add_f32_e32 v46, v51, v46
	v_add_f32_e32 v47, v48, v47
	v_mul_f32_e32 v48, v111, v53
	v_add_f32_e32 v46, v50, v46
	v_fmac_f32_e32 v48, v109, v49
	v_add_f32_e32 v46, v48, v46
	s_waitcnt lgkmcnt(0)
	v_mul_f32_e32 v48, v88, v74
	v_fmac_f32_e32 v48, v84, v54
	v_add_f32_e32 v47, v48, v47
	v_mul_f32_e32 v48, v122, v74
	v_fmac_f32_e32 v48, v120, v54
	v_add_f32_e32 v46, v48, v46
	v_mul_f32_e32 v48, v89, v75
	v_fmac_f32_e32 v48, v85, v55
	v_add_f32_e32 v47, v48, v47
	v_mul_f32_e32 v48, v123, v75
	v_fmac_f32_e32 v48, v121, v55
	v_add_f32_e32 v46, v48, v46
	v_mul_f32_e32 v48, v86, v76
	v_fmac_f32_e32 v48, v80, v56
	v_add_f32_e32 v54, v48, v47
	v_mul_f32_e32 v47, v118, v76
	v_fmac_f32_e32 v47, v116, v56
	v_add_f32_e32 v55, v47, v46
	ds_read_b128 v[46:49], v209
	ds_read_b128 v[50:53], v210
	v_mul_f32_e32 v56, v87, v77
	v_fmac_f32_e32 v56, v81, v57
	v_add_f32_e32 v54, v56, v54
	v_mul_f32_e32 v56, v119, v77
	v_fmac_f32_e32 v56, v117, v57
	s_waitcnt lgkmcnt(0)
	v_mul_f32_e32 v14, v14, v50
	v_add_f32_e32 v55, v56, v55
	v_mul_f32_e32 v56, v96, v50
	v_fmac_f32_e32 v14, v12, v46
	v_fmac_f32_e32 v56, v94, v46
	v_add_f32_e32 v12, v14, v55
	v_mul_f32_e32 v14, v97, v51
	v_mul_f32_e32 v15, v15, v51
	v_add_f32_e32 v54, v56, v54
	v_fmac_f32_e32 v14, v95, v47
	v_fmac_f32_e32 v15, v13, v47
	v_mul_f32_e32 v13, v92, v52
	v_mul_f32_e32 v10, v10, v52
	v_add_f32_e32 v14, v14, v54
	v_add_f32_e32 v12, v15, v12
	v_fmac_f32_e32 v13, v90, v48
	v_fmac_f32_e32 v10, v8, v48
	v_add_f32_e32 v46, v13, v14
	v_add_f32_e32 v8, v10, v12
	ds_read_b128 v[12:15], v211
	ds_read_b128 v[54:57], v212
	v_mul_f32_e32 v10, v93, v53
	v_mul_f32_e32 v11, v11, v53
	v_fmac_f32_e32 v10, v91, v49
	v_fmac_f32_e32 v11, v9, v49
	s_waitcnt lgkmcnt(0)
	v_mul_f32_e32 v9, v106, v54
	v_add_f32_e32 v10, v10, v46
	v_fmac_f32_e32 v9, v104, v12
	v_add_f32_e32 v9, v9, v10
	v_mul_f32_e32 v10, v20, v54
	v_add_f32_e32 v8, v11, v8
	v_fmac_f32_e32 v10, v18, v12
	v_add_f32_e32 v8, v10, v8
	v_mul_f32_e32 v10, v107, v55
	v_fmac_f32_e32 v10, v105, v13
	v_add_f32_e32 v9, v10, v9
	v_mul_f32_e32 v10, v21, v55
	v_cndmask_b32_e64 v11, v5, v38, s[6:7]
	v_fmac_f32_e32 v10, v19, v13
	ds_bpermute_b32 v11, v222, v11
	v_cndmask_b32_e64 v12, v24, v40, s[6:7]
	v_add_f32_e32 v8, v10, v8
	v_mul_f32_e32 v10, v102, v56
	ds_bpermute_b32 v12, v222, v12
	v_cndmask_b32_e64 v13, v26, v42, s[6:7]
	v_fmac_f32_e32 v10, v100, v14
	ds_bpermute_b32 v13, v222, v13
	v_add_f32_e32 v9, v10, v9
	v_mul_f32_e32 v10, v6, v56
	v_fmac_f32_e32 v10, v16, v14
	v_cndmask_b32_e64 v5, v38, v5, s[6:7]
	v_add_f32_e32 v8, v10, v8
	v_mul_f32_e32 v10, v103, v57
	s_waitcnt lgkmcnt(2)
; __device__ __forceinline__ float reduce16(const float (&p)[16], int lane) {
;     float a[8], b[4], c[2];
;     { const bool hi = (lane & 32) != 0;
; #pragma unroll
;       for (int k = 0; k < 8; ++k) { const float send = hi ? p[k] : p[k + 8], keep = hi ? p[k + 8] : p[k]; a[k] = keep + __shfl_xor(send, 32); } }
;     { const bool hi = (lane & 16) != 0;
; #pragma unroll
;       for (int k = 0; k < 4; ++k) { const float send = hi ? a[k] : a[k + 4], keep = hi ? a[k + 4] : a[k]; b[k] = keep + __shfl_xor(send, 16); } }
;     { const bool hi = (lane & 8) != 0;
; #pragma unroll
;       for (int k = 0; k < 2; ++k) { const float send = hi ? b[k] : b[k + 2], keep = hi ? b[k + 2] : b[k]; c[k] = keep + __shfl_xor(send, 8); } }
;     const bool hi4 = (lane & 4) != 0; const float send = hi4 ? c[0] : c[1], keep = hi4 ? c[1] : c[0];
;     float d = keep + __shfl_xor(send, 4);
;     d += __shfl_xor(d, 2); d += __shfl_xor(d, 1);
;     return d;
; }
; template <bool ZP, bool XF32, bool OUT8 = false>
; __device__ __forceinline__ void norm_phase(LAS unsigned char* lds, const void* xin, const float* gain, const float* sh, const float* sc, bf16* hout, const float* wzt, float* zout, int lane, int wave, int vcu, int G) {
;     ...
;             const float z0 = reduce16(p0, lane), z1 = reduce16(p1, lane);
;             if ((lane & 3) == 0) { const int rr = ((lane >> 5) & 1) * 8 + ((lane >> 4) & 1) * 4 + ((lane >> 3) & 1) * 2 + ((lane >> 2) & 1);
;                 zout[(size_t)m0 * 16 + rr] = z0; zout[(size_t)(m0 + 1) * 16 + rr] = z1; }
	v_add_f32_e32 v5, v5, v11
	v_cndmask_b32_e64 v11, v40, v24, s[6:7]
	v_fmac_f32_e32 v10, v101, v15
	s_waitcnt lgkmcnt(1)
	v_add_f32_e32 v11, v11, v12
	v_cndmask_b32_e64 v12, v42, v26, s[6:7]
	v_add_f32_e32 v9, v10, v9
	v_mul_f32_e32 v10, v7, v57
	s_waitcnt lgkmcnt(0)
	v_add_f32_e32 v12, v12, v13
	v_cndmask_b32_e64 v13, v28, v44, s[6:7]
	v_fmac_f32_e32 v10, v17, v15
	ds_bpermute_b32 v13, v222, v13
	v_cndmask_b32_e64 v15, v30, v128, s[6:7]
	ds_bpermute_b32 v15, v222, v15
	v_cndmask_b32_e64 v16, v32, v129, s[6:7]
	ds_bpermute_b32 v16, v222, v16
	v_cndmask_b32_e64 v14, v44, v28, s[6:7]
	s_waitcnt lgkmcnt(2)
	v_add_f32_e32 v13, v14, v13
	v_cndmask_b32_e64 v14, v128, v30, s[6:7]
	s_waitcnt lgkmcnt(1)
	v_add_f32_e32 v14, v14, v15
	v_cndmask_b32_e64 v15, v129, v32, s[6:7]
	s_waitcnt lgkmcnt(0)
	v_add_f32_e32 v15, v15, v16
	v_cndmask_b32_e64 v16, v34, v124, s[6:7]
	ds_bpermute_b32 v16, v222, v16
	v_cndmask_b32_e64 v18, v36, v9, s[6:7]
	ds_bpermute_b32 v18, v222, v18
	v_cndmask_b32_e64 v17, v124, v34, s[6:7]
	v_cndmask_b32_e64 v9, v9, v36, s[6:7]
	s_waitcnt lgkmcnt(1)
	v_add_f32_e32 v16, v17, v16
	v_cndmask_b32_e64 v19, v5, v14, s[8:9]
	s_waitcnt lgkmcnt(0)
	v_add_f32_e32 v9, v9, v18
	v_cndmask_b32_e64 v5, v14, v5, s[8:9]
	v_cndmask_b32_e64 v14, v11, v15, s[8:9]
	v_cndmask_b32_e64 v11, v15, v11, s[8:9]
	v_cndmask_b32_e64 v15, v12, v16, s[8:9]
	ds_bpermute_b32 v19, v221, v19
	ds_bpermute_b32 v15, v221, v15
	v_cndmask_b32_e64 v17, v13, v9, s[8:9]
	ds_bpermute_b32 v14, v221, v14
	ds_bpermute_b32 v17, v221, v17
	v_cndmask_b32_e64 v12, v16, v12, s[8:9]
	s_waitcnt lgkmcnt(3)
	v_add_f32_e32 v5, v5, v19
	s_waitcnt lgkmcnt(2)
	v_add_f32_e32 v12, v12, v15
	v_cndmask_b32_e64 v9, v9, v13, s[8:9]
	s_waitcnt lgkmcnt(1)
	v_add_f32_e32 v11, v11, v14
	s_waitcnt lgkmcnt(0)
	v_add_f32_e32 v9, v9, v17
	v_cndmask_b32_e64 v13, v5, v12, s[10:11]
	ds_bpermute_b32 v13, v220, v13
	v_cndmask_b32_e64 v14, v11, v9, s[10:11]
	ds_bpermute_b32 v14, v220, v14
	v_cndmask_b32_e64 v5, v12, v5, s[10:11]
	v_cndmask_b32_e64 v9, v9, v11, s[10:11]
	v_cndmask_b32_e64 v11, v22, v37, s[6:7]
	s_waitcnt lgkmcnt(1)
	v_add_f32_e32 v5, v5, v13
	ds_bpermute_b32 v11, v222, v11
	v_cndmask_b32_e64 v13, v23, v39, s[6:7]
	s_waitcnt lgkmcnt(1)
	v_add_f32_e32 v9, v9, v14
	ds_bpermute_b32 v13, v222, v13
	v_cndmask_b32_e64 v14, v25, v41, s[6:7]
	ds_bpermute_b32 v14, v222, v14
	v_cndmask_b32_e64 v12, v37, v22, s[6:7]
	s_waitcnt lgkmcnt(2)
	v_add_f32_e32 v11, v12, v11
	v_cndmask_b32_e64 v12, v39, v23, s[6:7]
	s_waitcnt lgkmcnt(1)
	v_add_f32_e32 v12, v12, v13
	v_cndmask_b32_e64 v13, v41, v25, s[6:7]
	s_waitcnt lgkmcnt(0)
	v_add_f32_e32 v13, v13, v14
	v_cndmask_b32_e64 v14, v27, v43, s[6:7]
	ds_bpermute_b32 v14, v222, v14
	v_cndmask_b32_e64 v16, v29, v45, s[6:7]
	ds_bpermute_b32 v16, v222, v16
	v_cndmask_b32_e64 v17, v31, v130, s[6:7]
	ds_bpermute_b32 v17, v222, v17
	v_cndmask_b32_e64 v15, v43, v27, s[6:7]
	s_waitcnt lgkmcnt(2)
	v_add_f32_e32 v14, v15, v14
	v_cndmask_b32_e64 v15, v45, v29, s[6:7]
	v_add_f32_e32 v8, v10, v8
	s_waitcnt lgkmcnt(1)
	v_add_f32_e32 v15, v15, v16
	v_cndmask_b32_e64 v16, v130, v31, s[6:7]
	s_waitcnt lgkmcnt(0)
	v_add_f32_e32 v16, v16, v17
	v_cndmask_b32_e64 v17, v33, v125, s[6:7]
	v_cndmask_b32_e64 v19, v35, v8, s[6:7]
	ds_bpermute_b32 v17, v222, v17
	ds_bpermute_b32 v19, v222, v19
	v_cndmask_b32_e64 v18, v125, v33, s[6:7]
	v_cndmask_b32_e64 v8, v8, v35, s[6:7]
	v_cndmask_b32_e64 v20, v11, v15, s[8:9]
	s_waitcnt lgkmcnt(1)
	v_add_f32_e32 v17, v18, v17
	s_waitcnt lgkmcnt(0)
	v_add_f32_e32 v8, v8, v19
	v_cndmask_b32_e64 v11, v15, v11, s[8:9]
	v_cndmask_b32_e64 v15, v12, v16, s[8:9]
	v_cndmask_b32_e64 v12, v16, v12, s[8:9]
	v_cndmask_b32_e64 v16, v13, v17, s[8:9]
	v_cndmask_b32_e64 v18, v14, v8, s[8:9]
	ds_bpermute_b32 v20, v221, v20
	ds_bpermute_b32 v15, v221, v15
	ds_bpermute_b32 v16, v221, v16
	ds_bpermute_b32 v18, v221, v18
	v_cndmask_b32_e64 v13, v17, v13, s[8:9]
	v_cndmask_b32_e64 v8, v8, v14, s[8:9]
	s_waitcnt lgkmcnt(3)
	v_add_f32_e32 v11, v11, v20
	s_waitcnt lgkmcnt(2)
	v_add_f32_e32 v12, v12, v15
	s_waitcnt lgkmcnt(1)
	v_add_f32_e32 v13, v13, v16
	s_waitcnt lgkmcnt(0)
	v_add_f32_e32 v8, v8, v18
	v_cndmask_b32_e64 v14, v11, v13, s[10:11]
	v_cndmask_b32_e64 v15, v12, v8, s[10:11]
	ds_bpermute_b32 v14, v220, v14
	ds_bpermute_b32 v15, v220, v15
	v_cndmask_b32_e64 v11, v13, v11, s[10:11]
	v_cndmask_b32_e64 v8, v8, v12, s[10:11]
	v_cndmask_b32_e64 v10, v5, v9, s[12:13]
	s_waitcnt lgkmcnt(1)
	v_add_f32_e32 v11, v11, v14
	s_waitcnt lgkmcnt(0)
	v_add_f32_e32 v8, v8, v15
	v_cndmask_b32_e64 v12, v11, v8, s[12:13]
	ds_bpermute_b32 v10, v219, v10
	ds_bpermute_b32 v12, v219, v12
	v_cndmask_b32_e64 v5, v9, v5, s[12:13]
	v_cndmask_b32_e64 v8, v8, v11, s[12:13]
	v_bfe_u32 v1, v6, 16, 1
	s_waitcnt lgkmcnt(1)
	v_add_f32_e32 v5, v5, v10
	s_waitcnt lgkmcnt(0)
	v_add_f32_e32 v8, v8, v12
	ds_bpermute_b32 v9, v218, v5
	ds_bpermute_b32 v10, v218, v8
	v_add3_u32 v1, v6, v1, s41
	v_lshrrev_b32_e32 v11, 16, v1
	s_waitcnt lgkmcnt(1)
	v_add_f32_e32 v1, v5, v9
	s_waitcnt lgkmcnt(0)
	v_add_f32_e32 v8, v8, v10
	ds_bpermute_b32 v6, v217, v1
	ds_bpermute_b32 v9, v217, v8
	v_bfe_u32 v5, v7, 16, 1
	v_add3_u32 v5, v7, v5, s41
	v_and_or_b32 v5, v5, s39, v11
	global_store_dwordx4 v[98:99], v[2:5], off offset:3072
	s_and_saveexec_b64 s[22:23], s[14:15]
	s_cbranch_execz .LBB0_1552
	s_lshl_b64 s[0:1], s[18:19], 6
	s_waitcnt lgkmcnt(1)
	v_add_f32_e32 v1, v1, v6
	v_lshl_add_u64 v[2:3], v[60:61], 0, s[0:1]
	s_lshl_b64 s[0:1], s[20:21], 6
	s_waitcnt lgkmcnt(0)
	v_add_f32_e32 v4, v8, v9
	global_store_dword v[2:3], v1, off
	v_lshl_add_u64 v[2:3], v[60:61], 0, s[0:1]
	global_store_dword v[2:3], v4, off
	s_branch .LBB0_1552
